# attention bodies (chunk-band quad incl. peeled copies, prompt/sample sliding-window, sample chunk-band): K and V^T fragment LDS reads software-pipelined with counted lgkmcnt instead of read->wait->MFM
# speedup vs baseline: 1.0045x; 1.0015x over previous
; #define LAS __attribute__((address_space(3)))
; #define MFMA32(a, b, cc) __builtin_amdgcn_mfma_f32_32x32x16_bf16((a), (b), (cc), 0, 0, 0)
; template <int MODE, class Src>
; DI void attn_item(LAS unsigned char* lds, const Src& src, const bf16_t* Qp  , bf16_t* Op  , int nband, int jj0, float sink_l2, const LAS float* tbl, int qbase, int tid) {
;     ...
;     for (int jj = jj0; jj < nband; ++jj) {
;         const bool last = (jj == nband - 1);
;         if (MODE) asm volatile("s_waitcnt vmcnt(8)" ::: "memory"); else asm volatile("s_waitcnt vmcnt(2)" ::: "memory");
;         __builtin_amdgcn_s_barrier(); asm volatile("" ::: "memory");
;         f32x16 s[2];
; #pragma unroll
;         for (int kb = 0; kb < 2; ++kb) {
; #pragma unroll
;             for (int i = 0; i < 16; ++i) s[kb][i] = 0.f;
; #pragma unroll
;             for (int ks = 0; ks < 8; ++ks) { const bf16x8 kf = *(const LAS bf16x8*)(Kt + 8192 * kb + ((32 * ks) ^ kx)); s[kb] = MFMA32(kf, qf[ks], s[kb]); }
;         }
;         asm volatile("s_waitcnt lgkmcnt(0)" ::: "memory"); __builtin_amdgcn_s_barrier(); asm volatile("" ::: "memory");
.LBB0_477:
	s_waitcnt vmcnt(2)
	s_barrier
	v_add_u32_e32 v88, v141, v143
	ds_read_b128 v[172:175], v88
	ds_read_b128 v[176:179], v146
	ds_read_b128 v[180:183], v147
	ds_read_b128 v[186:189], v148
	ds_read_b128 v[190:193], v149
	ds_read_b128 v[204:207], v150
	ds_read_b128 v[208:211], v151
	ds_read_b128 v[212:215], v152
	ds_read_b128 v[230:233], v88 offset:8192
	ds_read_b128 v[234:237], v146 offset:8192
	s_mov_b32 s42, s64
	s_add_i32 s64, s64, 1
	s_cmp_lg_u32 s42, 1
	s_cselect_b64 s[48:49], -1, 0
	s_waitcnt lgkmcnt(9)
	v_mfma_f32_32x32x16_bf16 v[68:83], v[172:175], v[100:103], 0
	ds_read_b128 v[172:175], v147 offset:8192
	s_cmp_eq_u32 s42, 1
	s_waitcnt lgkmcnt(9)
	v_mfma_f32_32x32x16_bf16 v[68:83], v[176:179], v[104:107], v[68:83]
	ds_read_b128 v[176:179], v148 offset:8192
	s_waitcnt lgkmcnt(9)
	v_mfma_f32_32x32x16_bf16 v[68:83], v[180:183], v[108:111], v[68:83]
	ds_read_b128 v[180:183], v149 offset:8192
	s_waitcnt lgkmcnt(9)
	v_mfma_f32_32x32x16_bf16 v[68:83], v[186:189], v[112:115], v[68:83]
	ds_read_b128 v[186:189], v150 offset:8192
	s_waitcnt lgkmcnt(9)
	v_mfma_f32_32x32x16_bf16 v[68:83], v[190:193], v[116:119], v[68:83]
	ds_read_b128 v[190:193], v151 offset:8192
	s_waitcnt lgkmcnt(9)
	v_mfma_f32_32x32x16_bf16 v[68:83], v[204:207], v[120:123], v[68:83]
	ds_read_b128 v[204:207], v152 offset:8192
	s_waitcnt lgkmcnt(9)
	v_mfma_f32_32x32x16_bf16 v[68:83], v[208:211], v[124:127], v[68:83]
	s_waitcnt lgkmcnt(8)
	v_mfma_f32_32x32x16_bf16 v[68:83], v[212:215], v[128:131], v[68:83]
	s_waitcnt lgkmcnt(7)
	v_mfma_f32_32x32x16_bf16 v[84:99], v[230:233], v[100:103], 0
	s_waitcnt lgkmcnt(6)
	v_mfma_f32_32x32x16_bf16 v[84:99], v[234:237], v[104:107], v[84:99]
	s_waitcnt lgkmcnt(5)
	v_mfma_f32_32x32x16_bf16 v[84:99], v[172:175], v[108:111], v[84:99]
	s_waitcnt lgkmcnt(4)
	v_mfma_f32_32x32x16_bf16 v[84:99], v[176:179], v[112:115], v[84:99]
	s_waitcnt lgkmcnt(3)
	v_mfma_f32_32x32x16_bf16 v[84:99], v[180:183], v[116:119], v[84:99]
	s_waitcnt lgkmcnt(2)
	v_mfma_f32_32x32x16_bf16 v[84:99], v[186:189], v[120:123], v[84:99]
	s_waitcnt lgkmcnt(1)
	v_mfma_f32_32x32x16_bf16 v[84:99], v[190:193], v[124:127], v[84:99]
	s_barrier
	s_waitcnt lgkmcnt(0)
	v_mfma_f32_32x32x16_bf16 v[84:99], v[204:207], v[128:131], v[84:99]
	s_cbranch_scc1 .LBB0_491
	s_cmp_lt_i32 s64, 1
	s_cselect_b64 s[42:43], -1, 0
	v_cndmask_b32_e64 v139, 0, 1, s[42:43]
	s_mov_b64 s[54:55], -1
	s_and_b64 vcc, exec, s[4:5]
	v_cmp_ne_u32_e64 s[42:43], 1, v139
	s_cbranch_vccz .LBB0_482
	s_mov_b64 s[50:51], 0x1a00
	s_and_b64 vcc, exec, s[42:43]
	s_mov_b64 s[52:53], s[34:35]
	s_cbranch_vccnz .LBB0_481
	s_ashr_i32 s45, s44, 31
	s_lshl_b64 s[50:51], s[44:45], 9
	s_add_u32 s52, s26, s50
	s_addc_u32 s53, s27, s51
	s_mov_b64 s[50:51], 0x100

; #define LAS __attribute__((address_space(3)))
; DI unsigned pk2(float a, float b) { f32x2 v = {a, b}; bf16v2 r = __builtin_convertvector(v, bf16v2); return __builtin_bit_cast(unsigned, r); }
; #define MFMA32(a, b, cc) __builtin_amdgcn_mfma_f32_32x32x16_bf16((a), (b), (cc), 0, 0, 0)
; template <int MODE, class Src>
; DI void attn_item(LAS unsigned char* lds, const Src& src, const bf16_t* Qp  , bf16_t* Op  , int nband, int jj0, float sink_l2, const LAS float* tbl, int qbase, int tid) {
;     ...
;         if (last) asm volatile("s_waitcnt vmcnt(0)" ::: "memory"); else { if (MODE) asm volatile("s_waitcnt vmcnt(8)" ::: "memory"); else asm volatile("s_waitcnt vmcnt(2)" ::: "memory"); }
;         __builtin_amdgcn_s_barrier(); asm volatile("" ::: "memory");
; #pragma unroll
;         for (int kb = 0; kb < 2; ++kb)
; #pragma unroll
;             for (int st = 0; st < 2; ++st) {
;                 u32x4 pp; pp.x = pk2(s[kb][8 * st + 0], s[kb][8 * st + 1]); pp.y = pk2(s[kb][8 * st + 2], s[kb][8 * st + 3]); pp.z = pk2(s[kb][8 * st + 4], s[kb][8 * st + 5]); pp.w = pk2(s[kb][8 * st + 6], s[kb][8 * st + 7]);
;                 const bf16x8 pf = __builtin_bit_cast(bf16x8, pp);
; #pragma unroll
;                 for (int db = 0; db < 4; ++db) {
;                     s16x4 v2[2];
; #pragma unroll
;                     for (int t = 0; t < 2; ++t) {
;                         const int f = (q << 2) | ((2 * t + h) & 3);
;                         v2[t] = __builtin_amdgcn_ds_read_tr16_b64_v4i16((LAS s16x4*)(Vt + 256 * (32 * kb + 16 * st + 8 * t) + 16 * ((4 * db + vlo) ^ f)));
;                     }
;                     const bf16x8 vf = __builtin_shufflevector(v2[0], v2[1], 0, 1, 2, 3, 4, 5, 6, 7);
;                     o[db] = MFMA32(vf, pf, o[db]);
;                 }
;             }
;         asm volatile("s_waitcnt lgkmcnt(0)" ::: "memory"); __builtin_amdgcn_s_barrier(); asm volatile("" ::: "memory");
.LBB0_497:
	s_barrier
	s_waitcnt vmcnt(0)
	ds_read_b64_tr_b16 v[180:181], v153
	ds_read_b64_tr_b16 v[182:183], v154 offset:2048
	ds_read_b64_tr_b16 v[186:187], v155
	ds_read_b64_tr_b16 v[188:189], v156 offset:2048
	ds_read_b64_tr_b16 v[190:191], v157
	ds_read_b64_tr_b16 v[192:193], v158 offset:2048
	ds_read_b64_tr_b16 v[204:205], v159
	ds_read_b64_tr_b16 v[206:207], v160 offset:2048
	ds_read_b64_tr_b16 v[208:209], v153 offset:4096
	ds_read_b64_tr_b16 v[210:211], v154 offset:6144
	ds_read_b64_tr_b16 v[212:213], v155 offset:4096
	ds_read_b64_tr_b16 v[214:215], v156 offset:6144
	ds_read_b64_tr_b16 v[230:231], v157 offset:4096
	ds_read_b64_tr_b16 v[232:233], v158 offset:6144
	v_cvt_pk_bf16_f32 v86, v145, v162
	v_cvt_pk_bf16_f32 v87, v167, v169
	v_cvt_pk_bf16_f32 v88, v171, v173
	v_cvt_pk_bf16_f32 v89, v175, v177
	v_cvt_pk_bf16_f32 v78, v78, v79
	v_cvt_pk_bf16_f32 v79, v80, v81
	s_waitcnt lgkmcnt(12)
	v_mfma_f32_32x32x16_bf16 v[52:67], v[180:183], v[86:89], v[52:67]
	ds_read_b64_tr_b16 v[234:235], v153 offset:8192
	ds_read_b64_tr_b16 v[236:237], v154 offset:10240
	v_cvt_pk_bf16_f32 v80, v82, v83
	v_cvt_pk_bf16_f32 v81, v84, v85
	v_cvt_pk_bf16_f32 v70, v70, v71
	v_cvt_pk_bf16_f32 v71, v72, v73
	v_cvt_pk_bf16_f32 v72, v74, v75
	v_cvt_pk_bf16_f32 v73, v76, v77
	s_waitcnt lgkmcnt(12)
	v_mfma_f32_32x32x16_bf16 v[36:51], v[186:189], v[86:89], v[36:51]
	ds_read_b64_tr_b16 v[180:181], v155 offset:8192
	ds_read_b64_tr_b16 v[182:183], v156 offset:10240
	s_andn2_b64 vcc, exec, s[48:49]
	s_waitcnt lgkmcnt(12)
	v_mfma_f32_32x32x16_bf16 v[20:35], v[190:193], v[86:89], v[20:35]
	ds_read_b64_tr_b16 v[186:187], v157 offset:8192
	ds_read_b64_tr_b16 v[188:189], v158 offset:10240
	s_waitcnt lgkmcnt(12)
	v_mfma_f32_32x32x16_bf16 v[4:19], v[204:207], v[86:89], v[4:19]
	ds_read_b64_tr_b16 v[190:191], v159 offset:4096
	ds_read_b64_tr_b16 v[192:193], v160 offset:6144
	v_cvt_pk_bf16_f32 v86, v161, v163
	v_cvt_pk_bf16_f32 v87, v168, v170
	v_cvt_pk_bf16_f32 v88, v172, v174
	v_cvt_pk_bf16_f32 v89, v176, v178
	s_nop 0
	s_waitcnt lgkmcnt(12)
	v_mfma_f32_32x32x16_bf16 v[52:67], v[208:211], v[86:89], v[52:67]
	ds_read_b64_tr_b16 v[204:205], v153 offset:12288
	ds_read_b64_tr_b16 v[206:207], v154 offset:14336
	s_waitcnt lgkmcnt(12)
	v_mfma_f32_32x32x16_bf16 v[36:51], v[212:215], v[86:89], v[36:51]
	ds_read_b64_tr_b16 v[208:209], v155 offset:12288
	ds_read_b64_tr_b16 v[210:211], v156 offset:14336
	s_waitcnt lgkmcnt(12)
	v_mfma_f32_32x32x16_bf16 v[20:35], v[230:233], v[86:89], v[20:35]
	ds_read_b64_tr_b16 v[212:213], v159 offset:8192
	ds_read_b64_tr_b16 v[214:215], v160 offset:10240
	s_waitcnt lgkmcnt(12)
	v_mfma_f32_32x32x16_bf16 v[52:67], v[234:237], v[78:81], v[52:67]
	ds_read_b64_tr_b16 v[230:231], v157 offset:12288
	ds_read_b64_tr_b16 v[232:233], v158 offset:14336
	s_waitcnt lgkmcnt(12)
	v_mfma_f32_32x32x16_bf16 v[36:51], v[180:183], v[78:81], v[36:51]
	ds_read_b64_tr_b16 v[234:235], v159 offset:12288
	ds_read_b64_tr_b16 v[236:237], v160 offset:14336
	s_waitcnt lgkmcnt(12)
	v_mfma_f32_32x32x16_bf16 v[20:35], v[186:189], v[78:81], v[20:35]
	s_waitcnt lgkmcnt(10)
	v_mfma_f32_32x32x16_bf16 v[4:19], v[190:193], v[86:89], v[4:19]
	s_waitcnt lgkmcnt(8)
	v_mfma_f32_32x32x16_bf16 v[52:67], v[204:207], v[70:73], v[52:67]
	s_waitcnt lgkmcnt(6)
	v_mfma_f32_32x32x16_bf16 v[36:51], v[208:211], v[70:73], v[36:51]
	s_waitcnt lgkmcnt(4)
	v_mfma_f32_32x32x16_bf16 v[4:19], v[212:215], v[78:81], v[4:19]
	s_waitcnt lgkmcnt(2)
	v_mfma_f32_32x32x16_bf16 v[20:35], v[230:233], v[70:73], v[20:35]
	s_barrier
	s_waitcnt lgkmcnt(0)
	v_mfma_f32_32x32x16_bf16 v[4:19], v[234:237], v[70:73], v[4:19]
	s_cbranch_vccnz .LBB0_476
	s_cmp_lt_i32 s64, 1
	s_cselect_b64 s[42:43], -1, 0
	v_cndmask_b32_e64 v70, 0, 1, s[42:43]
	s_mov_b64 s[48:49], 0x1a00
	s_and_b64 vcc, exec, s[40:41]
	v_cmp_ne_u32_e64 s[42:43], 1, v70
	s_mov_b64 s[52:53], s[46:47]
	s_mov_b64 s[50:51], 0x1a00
	s_cbranch_vccnz .LBB0_501
	s_and_b64 vcc, exec, s[42:43]
	s_mov_b64 s[52:53], s[38:39]
	s_cbranch_vccnz .LBB0_501
	s_ashr_i32 s45, s44, 31
	s_lshl_b64 s[50:51], s[44:45], 9
	s_add_u32 s52, s58, s50
	s_addc_u32 s53, s59, s51
	s_mov_b64 s[50:51], 0x100

; #define LAS __attribute__((address_space(3)))
; DI unsigned pk2(float a, float b) { f32x2 v = {a, b}; bf16v2 r = __builtin_convertvector(v, bf16v2); return __builtin_bit_cast(unsigned, r); }
; #define MFMA32(a, b, cc) __builtin_amdgcn_mfma_f32_32x32x16_bf16((a), (b), (cc), 0, 0, 0)
; DI void attn_quad(LAS unsigned char* lds, const bf16_t* Z, bf16_t* BR, int c0  , int head, const LAS float* tbl, int tid) {
;     ...
;         float ps = 0.f; const float eoff = bc - mrun;
; #pragma unroll
;         for (int kb = 0; kb < 2; ++kb)
; #pragma unroll
;             for (int i = 0; i < 16; ++i) { s[kb][i] = __builtin_amdgcn_exp2f(__builtin_fmaf(s[kb][i], esc, eoff)); ps += s[kb][i]; }
;         ps += __shfl_xor(ps, 32);
;         lrun += ps;
; #pragma unroll
;         for (int kb = 0; kb < 2; ++kb)
; #pragma unroll
;             for (int st = 0; st < 2; ++st) {
;                 u32x4 pp; pp.x = pk2(s[kb][8 * st + 0], s[kb][8 * st + 1]); pp.y = pk2(s[kb][8 * st + 2], s[kb][8 * st + 3]); pp.z = pk2(s[kb][8 * st + 4], s[kb][8 * st + 5]); pp.w = pk2(s[kb][8 * st + 6], s[kb][8 * st + 7]);
;                 const bf16x8 pf = __builtin_bit_cast(bf16x8, pp);
; #pragma unroll
;                 for (int db = 0; db < 4; ++db) {
;                     s16x4 v2[2];
; #pragma unroll
;                     for (int t = 0; t < 2; ++t) {
;                         const int f = (q << 2) | ((2 * t + h) & 3);
;                         v2[t] = __builtin_amdgcn_ds_read_tr16_b64_v4i16((LAS s16x4*)(Vt + 256 * (32 * kb + 16 * st + 8 * t) + 16 * ((4 * db + vlo) ^ f)));
;                     }
;                     const bf16x8 vf = __builtin_shufflevector(v2[0], v2[1], 0, 1, 2, 3, 4, 5, 6, 7);
;                     o[db] = MFMA32(vf, pf, o[db]);
;                 }
;             }
.LBB0_561:
	v_sub_f32_e32 v100, v100, v149
	v_fma_f32 v68, s23, v68, v100
	v_exp_f32_e32 v101, v68
	v_fma_f32 v69, s23, v69, v100
	v_exp_f32_e32 v102, v69
	v_fma_f32 v69, s23, v70, v100
	v_exp_f32_e32 v103, v69
	v_fma_f32 v69, s23, v71, v100
	v_exp_f32_e32 v104, v69
	v_fma_f32 v69, s23, v72, v100
	v_add_f32_e32 v68, 0, v101
	v_exp_f32_e32 v105, v69
	v_fma_f32 v69, s23, v73, v100
	v_add_f32_e32 v68, v102, v68
	v_exp_f32_e32 v106, v69
	v_fma_f32 v69, s23, v74, v100
	v_add_f32_e32 v68, v103, v68
	v_exp_f32_e32 v107, v69
	v_fma_f32 v69, s23, v75, v100
	v_add_f32_e32 v68, v104, v68
	v_exp_f32_e32 v108, v69
	v_fma_f32 v69, s23, v76, v100
	v_add_f32_e32 v68, v105, v68
	v_exp_f32_e32 v109, v69
	v_fma_f32 v69, s23, v77, v100
	v_add_f32_e32 v68, v106, v68
	v_exp_f32_e32 v110, v69
	v_fma_f32 v69, s23, v78, v100
	v_add_f32_e32 v68, v107, v68
	v_exp_f32_e32 v111, v69
	v_fma_f32 v69, s23, v79, v100
	v_add_f32_e32 v68, v108, v68
	v_exp_f32_e32 v112, v69
	v_fma_f32 v69, s23, v80, v100
	v_add_f32_e32 v68, v109, v68
	v_exp_f32_e32 v113, v69
	v_fma_f32 v69, s23, v81, v100
	v_add_f32_e32 v68, v110, v68
	v_exp_f32_e32 v114, v69
	v_fma_f32 v69, s23, v82, v100
	v_add_f32_e32 v68, v111, v68
	v_exp_f32_e32 v82, v69
	v_fma_f32 v69, s23, v83, v100
	v_add_f32_e32 v68, v112, v68
	v_exp_f32_e32 v83, v69
	v_fma_f32 v69, s23, v84, v100
	v_add_f32_e32 v68, v113, v68
	v_exp_f32_e32 v84, v69
	v_fma_f32 v69, s23, v85, v100
	v_add_f32_e32 v68, v114, v68
	v_exp_f32_e32 v85, v69
	v_fma_f32 v69, s23, v86, v100
	v_add_f32_e32 v68, v82, v68
	v_exp_f32_e32 v86, v69
	v_fma_f32 v69, s23, v87, v100
	v_add_f32_e32 v68, v83, v68
	v_exp_f32_e32 v87, v69
	v_fma_f32 v69, s23, v88, v100
	v_add_f32_e32 v68, v84, v68
	v_exp_f32_e32 v88, v69
	v_fma_f32 v69, s23, v89, v100
	v_add_f32_e32 v68, v85, v68
	v_exp_f32_e32 v89, v69
	v_fma_f32 v69, s23, v90, v100
	v_add_f32_e32 v68, v86, v68
	v_exp_f32_e32 v90, v69
	v_fma_f32 v69, s23, v91, v100
	v_add_f32_e32 v68, v87, v68
	v_exp_f32_e32 v91, v69
	v_add_f32_e32 v68, v88, v68
	v_add_f32_e32 v68, v89, v68
	v_add_f32_e32 v68, v90, v68
	v_add_f32_e32 v69, v91, v68
	v_fma_f32 v68, s23, v92, v100
	v_exp_f32_e32 v68, v68
	v_fma_f32 v75, s23, v98, v100
	v_exp_f32_e32 v92, v75
	v_cvt_pk_bf16_f32 v75, v103, v104
	v_add_f32_e32 v70, v68, v69
	v_fma_f32 v69, s23, v93, v100
	v_exp_f32_e32 v69, v69
	v_cvt_pk_bf16_f32 v76, v105, v106
	v_cvt_pk_bf16_f32 v77, v107, v108
	v_add_u32_e32 v98, v141, v174
	v_add_f32_e32 v71, v69, v70
	v_fma_f32 v70, s23, v94, v100
	v_exp_f32_e32 v70, v70
	v_add_u32_e32 v94, v141, v170
	s_waitcnt vmcnt(0)
	v_cvt_pk_bf16_f32 v68, v68, v69
	v_add_f32_e32 v72, v70, v71
	v_fma_f32 v71, s23, v95, v100
	v_exp_f32_e32 v71, v71
	v_add_u32_e32 v95, v141, v171
	ds_read_b64_tr_b16 v[116:117], v94
	ds_read_b64_tr_b16 v[118:119], v95 offset:2048
	v_add_f32_e32 v73, v71, v72
	v_fma_f32 v72, s23, v96, v100
	v_exp_f32_e32 v72, v72
	v_add_u32_e32 v96, v141, v172
	v_cvt_pk_bf16_f32 v69, v70, v71
	v_add_f32_e32 v74, v72, v73
	v_fma_f32 v73, s23, v97, v100
	v_exp_f32_e32 v73, v73
	v_fmac_f32_e32 v100, s23, v99
	v_exp_f32_e32 v93, v100
	v_add_u32_e32 v97, v141, v173
	ds_read_b64_tr_b16 v[120:121], v96
	ds_read_b64_tr_b16 v[122:123], v97 offset:2048
	v_add_f32_e32 v74, v73, v74
	v_add_f32_e32 v74, v92, v74
	v_add_f32_e32 v74, v93, v74
	ds_bpermute_b32 v2, v2, v74
	s_waitcnt lgkmcnt(0)
	v_add_u32_e32 v99, v141, v175
	ds_read_b64_tr_b16 v[132:133], v98
	ds_read_b64_tr_b16 v[134:135], v99 offset:2048
	v_add_u32_e32 v100, v141, v169
	v_cvt_pk_bf16_f32 v70, v72, v73
	v_cvt_pk_bf16_f32 v71, v92, v93
	v_add_f32_e32 v2, v74, v2
	v_cvt_pk_bf16_f32 v74, v101, v102
	v_add_u32_e32 v101, v141, v176
	ds_read_b64_tr_b16 v[152:153], v100
	ds_read_b64_tr_b16 v[154:155], v101 offset:2048
	ds_read_b64_tr_b16 v[156:157], v94 offset:4096
	ds_read_b64_tr_b16 v[158:159], v95 offset:6144
	ds_read_b64_tr_b16 v[186:187], v96 offset:4096
	ds_read_b64_tr_b16 v[188:189], v97 offset:6144
	ds_read_b64_tr_b16 v[190:191], v98 offset:4096
	ds_read_b64_tr_b16 v[192:193], v99 offset:6144
	v_add_f32_e32 v145, v145, v2
	s_waitcnt lgkmcnt(12)
	v_mfma_f32_32x32x16_bf16 v[52:67], v[116:119], v[74:77], v[52:67]
	ds_read_b64_tr_b16 v[204:205], v100 offset:4096
	ds_read_b64_tr_b16 v[206:207], v101 offset:6144
	s_waitcnt lgkmcnt(12)
	v_mfma_f32_32x32x16_bf16 v[36:51], v[120:123], v[74:77], v[36:51]
	ds_read_b64_tr_b16 v[116:117], v94 offset:8192
	ds_read_b64_tr_b16 v[118:119], v95 offset:10240
	s_waitcnt lgkmcnt(12)
	v_mfma_f32_32x32x16_bf16 v[20:35], v[132:135], v[74:77], v[20:35]
	ds_read_b64_tr_b16 v[120:121], v96 offset:8192
	ds_read_b64_tr_b16 v[122:123], v97 offset:10240
	s_waitcnt lgkmcnt(12)
	v_mfma_f32_32x32x16_bf16 v[4:19], v[152:155], v[74:77], v[4:19]
	ds_read_b64_tr_b16 v[132:133], v98 offset:8192
	ds_read_b64_tr_b16 v[134:135], v99 offset:10240
	v_cvt_pk_bf16_f32 v74, v109, v110
	v_cvt_pk_bf16_f32 v75, v111, v112
	v_cvt_pk_bf16_f32 v76, v113, v114
	v_cvt_pk_bf16_f32 v77, v82, v83
	s_nop 0
	s_waitcnt lgkmcnt(12)
	v_mfma_f32_32x32x16_bf16 v[52:67], v[156:159], v[74:77], v[52:67]
	ds_read_b64_tr_b16 v[152:153], v100 offset:8192
	ds_read_b64_tr_b16 v[154:155], v101 offset:10240
	s_waitcnt lgkmcnt(12)
	v_mfma_f32_32x32x16_bf16 v[36:51], v[186:189], v[74:77], v[36:51]
	ds_read_b64_tr_b16 v[156:157], v94 offset:12288
	ds_read_b64_tr_b16 v[158:159], v95 offset:14336
	s_waitcnt lgkmcnt(12)
	v_mfma_f32_32x32x16_bf16 v[20:35], v[190:193], v[74:77], v[20:35]
	ds_read_b64_tr_b16 v[186:187], v96 offset:12288
	ds_read_b64_tr_b16 v[188:189], v97 offset:14336
	s_waitcnt lgkmcnt(12)
	v_mfma_f32_32x32x16_bf16 v[4:19], v[204:207], v[74:77], v[4:19]
	ds_read_b64_tr_b16 v[190:191], v98 offset:12288
	ds_read_b64_tr_b16 v[192:193], v99 offset:14336
	v_cvt_pk_bf16_f32 v74, v84, v85
	v_cvt_pk_bf16_f32 v75, v86, v87
	v_cvt_pk_bf16_f32 v76, v88, v89
	v_cvt_pk_bf16_f32 v77, v90, v91
	s_nop 0
	s_waitcnt lgkmcnt(12)
	v_mfma_f32_32x32x16_bf16 v[52:67], v[116:119], v[74:77], v[52:67]
	ds_read_b64_tr_b16 v[204:205], v100 offset:12288
	ds_read_b64_tr_b16 v[206:207], v101 offset:14336
	s_waitcnt lgkmcnt(12)
	v_mfma_f32_32x32x16_bf16 v[36:51], v[120:123], v[74:77], v[36:51]
	s_waitcnt lgkmcnt(10)
	v_mfma_f32_32x32x16_bf16 v[20:35], v[132:135], v[74:77], v[20:35]
	s_waitcnt lgkmcnt(8)
	v_mfma_f32_32x32x16_bf16 v[4:19], v[152:155], v[74:77], v[4:19]
	s_waitcnt lgkmcnt(6)
	v_mfma_f32_32x32x16_bf16 v[52:67], v[156:159], v[68:71], v[52:67]
	s_waitcnt lgkmcnt(4)
	v_mfma_f32_32x32x16_bf16 v[36:51], v[186:189], v[68:71], v[36:51]
	s_waitcnt lgkmcnt(2)
	v_mfma_f32_32x32x16_bf16 v[20:35], v[190:193], v[68:71], v[20:35]
	s_waitcnt lgkmcnt(0)
	v_mfma_f32_32x32x16_bf16 v[4:19], v[204:207], v[68:71], v[4:19]

; #define LAS __attribute__((address_space(3)))
; DI unsigned pk2(float a, float b) { f32x2 v = {a, b}; bf16v2 r = __builtin_convertvector(v, bf16v2); return __builtin_bit_cast(unsigned, r); }
; #define MFMA32(a, b, cc) __builtin_amdgcn_mfma_f32_32x32x16_bf16((a), (b), (cc), 0, 0, 0)
; DI void attn_quad(LAS unsigned char* lds, const bf16_t* Z, bf16_t* BR, int c0  , int head, const LAS float* tbl, int tid) {
;     ...
;         float ps = 0.f; const float eoff = bc - mrun;
; #pragma unroll
;         for (int kb = 0; kb < 2; ++kb)
; #pragma unroll
;             for (int i = 0; i < 16; ++i) { s[kb][i] = __builtin_amdgcn_exp2f(__builtin_fmaf(s[kb][i], esc, eoff)); ps += s[kb][i]; }
;         ps += __shfl_xor(ps, 32);
;         lrun += ps;
; #pragma unroll
;         for (int kb = 0; kb < 2; ++kb)
; #pragma unroll
;             for (int st = 0; st < 2; ++st) {
;                 u32x4 pp; pp.x = pk2(s[kb][8 * st + 0], s[kb][8 * st + 1]); pp.y = pk2(s[kb][8 * st + 2], s[kb][8 * st + 3]); pp.z = pk2(s[kb][8 * st + 4], s[kb][8 * st + 5]); pp.w = pk2(s[kb][8 * st + 6], s[kb][8 * st + 7]);
;                 const bf16x8 pf = __builtin_bit_cast(bf16x8, pp);
; #pragma unroll
;                 for (int db = 0; db < 4; ++db) {
;                     s16x4 v2[2];
; #pragma unroll
;                     for (int t = 0; t < 2; ++t) {
;                         const int f = (q << 2) | ((2 * t + h) & 3);
;                         v2[t] = __builtin_amdgcn_ds_read_tr16_b64_v4i16((LAS s16x4*)(Vt + 256 * (32 * kb + 16 * st + 8 * t) + 16 * ((4 * db + vlo) ^ f)));
;                     }
;                     const bf16x8 vf = __builtin_shufflevector(v2[0], v2[1], 0, 1, 2, 3, 4, 5, 6, 7);
;                     o[db] = MFMA32(vf, pf, o[db]);
;                 }
;             }
.LBB0_564:
	v_sub_f32_e32 v137, v137, v149
	v_fma_f32 v68, s48, v68, v137
	v_exp_f32_e32 v154, v68
	v_fma_f32 v69, s48, v69, v137
	v_exp_f32_e32 v155, v69
	v_fma_f32 v69, s48, v70, v137
	v_exp_f32_e32 v156, v69
	v_fma_f32 v69, s48, v71, v137
	v_exp_f32_e32 v157, v69
	v_fma_f32 v69, s48, v72, v137
	v_add_f32_e32 v68, 0, v154
	v_exp_f32_e32 v158, v69
	v_fma_f32 v69, s48, v73, v137
	v_add_f32_e32 v68, v155, v68
	v_exp_f32_e32 v159, v69
	v_fma_f32 v69, s48, v74, v137
	v_add_f32_e32 v68, v156, v68
	v_exp_f32_e32 v74, v69
	v_fma_f32 v69, s48, v75, v137
	v_add_f32_e32 v68, v157, v68
	v_exp_f32_e32 v75, v69
	v_fma_f32 v69, s48, v76, v137
	v_add_f32_e32 v68, v158, v68
	v_exp_f32_e32 v184, v69
	v_fma_f32 v69, s48, v77, v137
	v_add_f32_e32 v68, v159, v68
	v_exp_f32_e32 v77, v69
	v_fma_f32 v69, s48, v78, v137
	v_add_f32_e32 v68, v74, v68
	v_exp_f32_e32 v185, v69
	v_fma_f32 v69, s48, v79, v137
	v_add_f32_e32 v68, v75, v68
	v_exp_f32_e32 v186, v69
	v_fma_f32 v69, s48, v80, v137
	v_add_f32_e32 v68, v184, v68
	v_exp_f32_e32 v187, v69
	v_fma_f32 v69, s48, v81, v137
	v_add_f32_e32 v68, v77, v68
	v_exp_f32_e32 v188, v69
	v_fma_f32 v69, s48, v82, v137
	v_add_f32_e32 v68, v185, v68
	v_exp_f32_e32 v189, v69
	v_fma_f32 v69, s48, v83, v137
	v_add_f32_e32 v68, v186, v68
	v_exp_f32_e32 v190, v69
	v_fma_f32 v69, s48, v84, v137
	v_add_f32_e32 v68, v187, v68
	v_exp_f32_e32 v191, v69
	v_fma_f32 v69, s48, v85, v137
	v_add_f32_e32 v68, v188, v68
	v_exp_f32_e32 v192, v69
	v_fma_f32 v69, s48, v86, v137
	v_add_f32_e32 v68, v189, v68
	v_exp_f32_e32 v86, v69
	v_fma_f32 v69, s48, v87, v137
	v_add_f32_e32 v68, v190, v68
	v_exp_f32_e32 v87, v69
	v_fma_f32 v69, s48, v88, v137
	v_add_f32_e32 v68, v191, v68
	v_exp_f32_e32 v88, v69
	v_fma_f32 v69, s48, v89, v137
	v_add_f32_e32 v68, v192, v68
	v_exp_f32_e32 v89, v69
	v_fma_f32 v69, s48, v90, v137
	v_add_f32_e32 v68, v86, v68
	v_exp_f32_e32 v90, v69
	v_fma_f32 v69, s48, v91, v137
	v_add_f32_e32 v68, v87, v68
	v_exp_f32_e32 v91, v69
	v_add_f32_e32 v68, v88, v68
	v_add_f32_e32 v68, v89, v68
	v_add_f32_e32 v68, v90, v68
	v_add_f32_e32 v69, v91, v68
	v_fma_f32 v68, s48, v92, v137
	v_exp_f32_e32 v68, v68
	v_fma_f32 v78, s48, v98, v137
	v_exp_f32_e32 v92, v78
	v_add3_u32 v153, s47, v183, v179
	v_add_f32_e32 v70, v68, v69
	v_fma_f32 v69, s48, v93, v137
	v_exp_f32_e32 v69, v69
	v_cvt_pk_bf16_f32 v81, v74, v75
	v_add_u32_e32 v74, v153, v170
	v_add_u32_e32 v75, v153, v171
	v_add_f32_e32 v71, v69, v70
	v_fma_f32 v70, s48, v94, v137
	v_exp_f32_e32 v70, v70
	s_waitcnt vmcnt(0)
	ds_read_b64_tr_b16 v[204:205], v74 offset:16384
	ds_read_b64_tr_b16 v[206:207], v75 offset:18432
	v_cvt_pk_bf16_f32 v79, v156, v157
	v_add_f32_e32 v72, v70, v71
	v_fma_f32 v71, s48, v95, v137
	v_exp_f32_e32 v71, v71
	v_cvt_pk_bf16_f32 v80, v158, v159
	v_add_u32_e32 v94, v153, v172
	v_add_u32_e32 v95, v153, v173
	ds_read_b64_tr_b16 v[208:209], v94 offset:16384
	ds_read_b64_tr_b16 v[210:211], v95 offset:18432
	v_add_f32_e32 v73, v71, v72
	v_fma_f32 v72, s48, v96, v137
	v_exp_f32_e32 v72, v72
	v_add_u32_e32 v96, v153, v174
	v_add_u32_e32 v98, v153, v169
	v_cvt_pk_bf16_f32 v68, v68, v69
	v_add_f32_e32 v76, v72, v73
	v_fma_f32 v73, s48, v97, v137
	v_exp_f32_e32 v73, v73
	v_fmac_f32_e32 v137, s48, v99
	v_exp_f32_e32 v93, v137
	v_add_u32_e32 v97, v153, v175
	ds_read_b64_tr_b16 v[212:213], v96 offset:16384
	ds_read_b64_tr_b16 v[214:215], v97 offset:18432
	v_add_f32_e32 v76, v73, v76
	v_add_f32_e32 v76, v92, v76
	v_add_f32_e32 v76, v93, v76
	ds_bpermute_b32 v78, v152, v76
	s_waitcnt lgkmcnt(0)
	v_add_u32_e32 v99, v153, v176
	ds_read_b64_tr_b16 v[230:231], v98 offset:16384
	ds_read_b64_tr_b16 v[232:233], v99 offset:18432
	ds_read_b64_tr_b16 v[234:235], v74 offset:20480
	ds_read_b64_tr_b16 v[236:237], v75 offset:22528
	ds_read_b64_tr_b16 v[238:239], v94 offset:20480
	ds_read_b64_tr_b16 v[240:241], v95 offset:22528
	ds_read_b64_tr_b16 v[242:243], v96 offset:20480
	ds_read_b64_tr_b16 v[244:245], v97 offset:22528
	v_cvt_pk_bf16_f32 v69, v70, v71
	v_cvt_pk_bf16_f32 v70, v72, v73
	v_cvt_pk_bf16_f32 v71, v92, v93
	v_add_f32_e32 v76, v76, v78
	v_cvt_pk_bf16_f32 v78, v154, v155
	v_add_f32_e32 v145, v145, v76
	s_nop 0
	s_waitcnt lgkmcnt(12)
	v_mfma_f32_32x32x16_bf16 v[52:67], v[204:207], v[78:81], v[52:67]
	ds_read_b64_tr_b16 v[246:247], v98 offset:20480
	ds_read_b64_tr_b16 v[248:249], v99 offset:22528
	s_waitcnt lgkmcnt(12)
	v_mfma_f32_32x32x16_bf16 v[36:51], v[208:211], v[78:81], v[36:51]
	ds_read_b64_tr_b16 v[204:205], v74 offset:24576
	ds_read_b64_tr_b16 v[206:207], v75 offset:26624
	s_waitcnt lgkmcnt(12)
	v_mfma_f32_32x32x16_bf16 v[20:35], v[212:215], v[78:81], v[20:35]
	ds_read_b64_tr_b16 v[208:209], v94 offset:24576
	ds_read_b64_tr_b16 v[210:211], v95 offset:26624
	s_waitcnt lgkmcnt(12)
	v_mfma_f32_32x32x16_bf16 v[4:19], v[230:233], v[78:81], v[4:19]
	ds_read_b64_tr_b16 v[212:213], v96 offset:24576
	ds_read_b64_tr_b16 v[214:215], v97 offset:26624
	v_cvt_pk_bf16_f32 v78, v184, v77
	v_cvt_pk_bf16_f32 v79, v185, v186
	v_cvt_pk_bf16_f32 v80, v187, v188
	v_cvt_pk_bf16_f32 v81, v189, v190
	s_nop 0
	s_waitcnt lgkmcnt(12)
	v_mfma_f32_32x32x16_bf16 v[52:67], v[234:237], v[78:81], v[52:67]
	ds_read_b64_tr_b16 v[230:231], v74 offset:28672
	ds_read_b64_tr_b16 v[232:233], v75 offset:30720
	s_waitcnt lgkmcnt(12)
	v_mfma_f32_32x32x16_bf16 v[36:51], v[238:241], v[78:81], v[36:51]
	ds_read_b64_tr_b16 v[234:235], v94 offset:28672
	ds_read_b64_tr_b16 v[236:237], v95 offset:30720
	s_waitcnt lgkmcnt(12)
	v_mfma_f32_32x32x16_bf16 v[20:35], v[242:245], v[78:81], v[20:35]
	ds_read_b64_tr_b16 v[238:239], v98 offset:24576
	ds_read_b64_tr_b16 v[240:241], v99 offset:26624
	s_waitcnt lgkmcnt(12)
	v_mfma_f32_32x32x16_bf16 v[4:19], v[246:249], v[78:81], v[4:19]
	ds_read_b64_tr_b16 v[242:243], v96 offset:28672
	ds_read_b64_tr_b16 v[244:245], v97 offset:30720
	v_cvt_pk_bf16_f32 v78, v191, v192
	v_cvt_pk_bf16_f32 v79, v86, v87
	v_cvt_pk_bf16_f32 v80, v88, v89
	v_cvt_pk_bf16_f32 v81, v90, v91
	s_nop 0
	s_waitcnt lgkmcnt(12)
	v_mfma_f32_32x32x16_bf16 v[52:67], v[204:207], v[78:81], v[52:67]
	ds_read_b64_tr_b16 v[246:247], v98 offset:28672
	ds_read_b64_tr_b16 v[248:249], v99 offset:30720
	s_waitcnt lgkmcnt(12)
	v_mfma_f32_32x32x16_bf16 v[36:51], v[208:211], v[78:81], v[36:51]
	s_waitcnt lgkmcnt(10)
	v_mfma_f32_32x32x16_bf16 v[20:35], v[212:215], v[78:81], v[20:35]
	s_waitcnt lgkmcnt(8)
	v_mfma_f32_32x32x16_bf16 v[52:67], v[230:233], v[68:71], v[52:67]
	s_waitcnt lgkmcnt(6)
	v_mfma_f32_32x32x16_bf16 v[36:51], v[234:237], v[68:71], v[36:51]
	s_waitcnt lgkmcnt(4)
	v_mfma_f32_32x32x16_bf16 v[4:19], v[238:241], v[78:81], v[4:19]
	s_waitcnt lgkmcnt(2)
	v_mfma_f32_32x32x16_bf16 v[20:35], v[242:245], v[68:71], v[20:35]
	s_waitcnt lgkmcnt(0)
	v_mfma_f32_32x32x16_bf16 v[4:19], v[246:249], v[68:71], v[4:19]

; #define LAS __attribute__((address_space(3)))
; #define MFMA32(a, b, cc) __builtin_amdgcn_mfma_f32_32x32x16_bf16((a), (b), (cc), 0, 0, 0)
; DI void attn_quad(LAS unsigned char* lds, const bf16_t* Z, bf16_t* BR, int c0  , int head, const LAS float* tbl, int tid) {
;     ...
;         const int jj = j - qc;
;         if (jj < 0 || jj > 8) continue;
;         const LAS unsigned char* Kt = lds + (j & 3) * 32768 + 256 * r;
;         const LAS unsigned char* Vt = lds + (j & 3) * 32768 + 16384 + 256 * (4 * h + q) + 8 * (p & 1);
;         f32x16 s[2];
; #pragma unroll
;         for (int kb = 0; kb < 2; ++kb) {
; #pragma unroll
;             for (int i = 0; i < 16; ++i) s[kb][i] = 0.f;
; #pragma unroll
;             for (int ks = 0; ks < 8; ++ks) { const bf16x8 kf = *(const LAS bf16x8*)(Kt + 8192 * kb + ((32 * ks) ^ kx)); s[kb] = MFMA32(kf, qf[ks], s[kb]); }
;         }
;         const bool cb = jj <= 5; const float bc = cb ? tbl[256] : 0.f, esc = cb ? sc : 1.0f;
.LBB0_572:
	s_add_i32 s4, s46, s42
	s_cmp_gt_u32 s4, 8
	s_cbranch_scc1 .LBB0_565
	s_add_i32 s5, s43, 0xfffe8000
	s_and_b32 s5, s5, 0x18000
	s_add_i32 s47, s5, 0
	v_add_u32_e32 v88, s47, v178
	v_add_u32_e32 v89, v88, v161
	v_add_u32_e32 v137, v88, v162
	v_add_u32_e32 v156, v88, v163
	v_add_u32_e32 v157, v88, v164
	v_add_u32_e32 v158, v88, v165
	v_add_u32_e32 v159, v88, v166
	v_add_u32_e32 v184, v88, v167
	v_add_u32_e32 v185, v88, v168
	ds_read_b128 v[186:189], v89
	ds_read_b128 v[190:193], v137
	ds_read_b128 v[204:207], v156
	ds_read_b128 v[208:211], v157
	ds_read_b128 v[212:215], v158
	ds_read_b128 v[230:233], v159
	ds_read_b128 v[234:237], v184
	ds_read_b128 v[238:241], v185
	ds_read_b128 v[242:245], v89 offset:8192
	s_cmp_gt_u32 s4, 5
	s_cselect_b64 s[4:5], -1, 0
	s_and_b64 vcc, exec, s[4:5]
	s_waitcnt lgkmcnt(8)
	v_mfma_f32_32x32x16_bf16 v[68:83], v[186:189], v[128:131], 0
	ds_read_b128 v[246:249], v137 offset:8192
	s_waitcnt lgkmcnt(8)
	v_mfma_f32_32x32x16_bf16 v[68:83], v[190:193], v[124:127], v[68:83]
	ds_read_b128 v[186:189], v156 offset:8192
	s_waitcnt lgkmcnt(8)
	v_mfma_f32_32x32x16_bf16 v[68:83], v[204:207], v[120:123], v[68:83]
	ds_read_b128 v[190:193], v157 offset:8192
	s_waitcnt lgkmcnt(8)
	v_mfma_f32_32x32x16_bf16 v[68:83], v[208:211], v[116:119], v[68:83]
	ds_read_b128 v[204:207], v158 offset:8192
	s_waitcnt lgkmcnt(8)
	v_mfma_f32_32x32x16_bf16 v[68:83], v[212:215], v[112:115], v[68:83]
	ds_read_b128 v[208:211], v159 offset:8192
	s_waitcnt lgkmcnt(8)
	v_mfma_f32_32x32x16_bf16 v[68:83], v[230:233], v[108:111], v[68:83]
	ds_read_b128 v[212:215], v184 offset:8192
	s_waitcnt lgkmcnt(8)
	v_mfma_f32_32x32x16_bf16 v[68:83], v[234:237], v[104:107], v[68:83]
	ds_read_b128 v[230:233], v185 offset:8192
	s_waitcnt lgkmcnt(8)
	v_mfma_f32_32x32x16_bf16 v[68:83], v[238:241], v[100:103], v[68:83]
	s_waitcnt lgkmcnt(7)
	v_mfma_f32_32x32x16_bf16 v[84:99], v[242:245], v[128:131], 0
	s_waitcnt lgkmcnt(6)
	v_mfma_f32_32x32x16_bf16 v[84:99], v[246:249], v[124:127], v[84:99]
	s_waitcnt lgkmcnt(5)
	v_mfma_f32_32x32x16_bf16 v[84:99], v[186:189], v[120:123], v[84:99]
	s_waitcnt lgkmcnt(4)
	v_mfma_f32_32x32x16_bf16 v[84:99], v[190:193], v[116:119], v[84:99]
	s_waitcnt lgkmcnt(3)
	v_mfma_f32_32x32x16_bf16 v[84:99], v[204:207], v[112:115], v[84:99]
	s_waitcnt lgkmcnt(2)
	v_mfma_f32_32x32x16_bf16 v[84:99], v[208:211], v[108:111], v[84:99]
	s_waitcnt lgkmcnt(1)
	v_mfma_f32_32x32x16_bf16 v[84:99], v[212:215], v[104:107], v[84:99]
	s_waitcnt lgkmcnt(0)
	v_mfma_f32_32x32x16_bf16 v[84:99], v[230:233], v[100:103], v[84:99]
	s_cbranch_vccnz .LBB0_575
	v_mov_b32_e32 v137, s22
	ds_read_b32 v137, v137 offset:1024
	s_mov_b32 s48, 0x3e0293ee
	s_andn2_b64 vcc, exec, s[4:5]
	s_cbranch_vccz .LBB0_576
	s_branch .LBB0_577

; #define LAS __attribute__((address_space(3)))
; #define MFMA32(a, b, cc) __builtin_amdgcn_mfma_f32_32x32x16_bf16((a), (b), (cc), 0, 0, 0)
; DI void attn_quad(LAS unsigned char* lds, const bf16_t* Z, bf16_t* BR, int c0  , int head, const LAS float* tbl, int tid) {
;     ...
;     for (int j = j0; j < 12; ++j) {
;         if (j + 2 < 12) asm volatile("s_waitcnt vmcnt(8)" ::: "memory"); else if (j + 1 < 12) asm volatile("s_waitcnt vmcnt(4)" ::: "memory"); else asm volatile("s_waitcnt vmcnt(0)" ::: "memory");
;         asm volatile("s_waitcnt lgkmcnt(0)" ::: "memory"); __builtin_amdgcn_s_barrier(); asm volatile("" ::: "memory");
;         if (j + 3 < 12) AQ_ISSUE(j + 3);
;         const int jj = j - qc;
;         if (jj < 0 || jj > 8) continue;
;         const LAS unsigned char* Kt = lds + (j & 3) * 32768 + 256 * r;
;         const LAS unsigned char* Vt = lds + (j & 3) * 32768 + 16384 + 256 * (4 * h + q) + 8 * (p & 1);
;         f32x16 s[2];
; #pragma unroll
;         for (int kb = 0; kb < 2; ++kb) {
; #pragma unroll
;             for (int i = 0; i < 16; ++i) s[kb][i] = 0.f;
; #pragma unroll
;             for (int ks = 0; ks < 8; ++ks) { const bf16x8 kf = *(const LAS bf16x8*)(Kt + 8192 * kb + ((32 * ks) ^ kx)); s[kb] = MFMA32(kf, qf[ks], s[kb]); }
;         }
;         const bool cb = jj <= 5; const float bc = cb ? tbl[256] : 0.f, esc = cb ? sc : 1.0f;
;         if (!cb) {
; #pragma unroll
;             for (int kb = 0; kb < 2; ++kb) {
;                 const int dbase = qbase + r - kb * 32 - 4 * h + (8 - jj) * 64 + 128;
; #pragma unroll
;                 for (int i = 0; i < 16; ++i) { int idx = dbase - ((i & 3) + 8 * (i >> 2)); idx = idx > 256 ? 256 : idx; idx = idx < 0 ? 0 : idx; s[kb][i] = s[kb][i] * sc + tbl[idx]; }
.LBB0_579:
	s_waitcnt vmcnt(4)
	v_or_b32_e32 v2, s27, v138
	s_waitcnt lgkmcnt(0)
	s_barrier
	v_sub_u32_e32 v2, v2, v139
	s_sub_i32 s27, 10, s23
	v_add_u32_e32 v206, 0x280, v2
	v_add_u32_e32 v205, 0x27f, v2
	v_add_u32_e32 v204, 0x27e, v2
	v_add_u32_e32 v197, 0x27d, v2
	v_add_u32_e32 v195, 0x278, v2
	v_add_u32_e32 v194, 0x277, v2
	v_add_u32_e32 v193, 0x276, v2
	v_add_u32_e32 v192, 0x275, v2
	v_add_u32_e32 v191, 0x270, v2
	v_add_u32_e32 v190, 0x26f, v2
	v_add_u32_e32 v189, 0x26e, v2
	v_add_u32_e32 v188, 0x26d, v2
	v_add_u32_e32 v187, 0x268, v2
	v_add_u32_e32 v186, 0x267, v2
	v_add_u32_e32 v185, 0x266, v2
	v_add_u32_e32 v184, 0x265, v2
	v_add_u32_e32 v159, 0x260, v2
	v_add_u32_e32 v158, 0x25f, v2
	v_add_u32_e32 v157, 0x25e, v2
	v_add_u32_e32 v156, 0x25d, v2
	v_add_u32_e32 v155, 0x258, v2
	v_add_u32_e32 v154, 0x257, v2
	v_add_u32_e32 v153, 0x256, v2
	v_add_u32_e32 v152, 0x255, v2
	v_add_u32_e32 v151, 0x250, v2
	v_add_u32_e32 v137, 0x24f, v2
	v_add_u32_e32 v136, 0x24e, v2
	v_add_u32_e32 v135, 0x24d, v2
	v_add_u32_e32 v134, 0x248, v2
	v_add_u32_e32 v133, 0x247, v2
	v_add_u32_e32 v132, 0x246, v2
	v_add_u32_e32 v2, 0x245, v2
	s_cmp_gt_u32 s27, 8
	s_cbranch_scc1 .LBB0_587
	v_add_u32_e32 v88, v142, v161
	ds_read_b128 v[230:233], v88
	v_add_u32_e32 v207, v142, v162
	ds_read_b128 v[234:237], v207
	v_add_u32_e32 v212, v142, v163
	ds_read_b128 v[238:241], v212
	v_add_u32_e32 v213, v142, v164
	ds_read_b128 v[242:245], v213
	v_add_u32_e32 v214, v142, v165
	ds_read_b128 v[246:249], v214
	v_add_u32_e32 v215, v142, v166
	v_add_u32_e32 v216, v142, v167
	v_add_u32_e32 v217, v142, v168
	s_waitcnt lgkmcnt(4)
	v_mfma_f32_32x32x16_bf16 v[68:83], v[230:233], v[128:131], 0
	ds_read_b128 v[230:233], v215
	s_cmp_gt_u32 s27, 5
	s_cselect_b64 s[4:5], -1, 0
	s_and_b64 vcc, exec, s[4:5]
	s_waitcnt lgkmcnt(4)
	v_mfma_f32_32x32x16_bf16 v[68:83], v[234:237], v[124:127], v[68:83]
	ds_read_b128 v[234:237], v216
	s_waitcnt lgkmcnt(4)
	v_mfma_f32_32x32x16_bf16 v[68:83], v[238:241], v[120:123], v[68:83]
	ds_read_b128 v[238:241], v217
	s_waitcnt lgkmcnt(4)
	v_mfma_f32_32x32x16_bf16 v[68:83], v[242:245], v[116:119], v[68:83]
	ds_read_b128 v[242:245], v88 offset:8192
	s_waitcnt lgkmcnt(4)
	v_mfma_f32_32x32x16_bf16 v[68:83], v[246:249], v[112:115], v[68:83]
	ds_read_b128 v[246:249], v207 offset:8192
	s_waitcnt lgkmcnt(4)
	v_mfma_f32_32x32x16_bf16 v[68:83], v[230:233], v[108:111], v[68:83]
	ds_read_b128 v[230:233], v212 offset:8192
	s_waitcnt lgkmcnt(4)
	v_mfma_f32_32x32x16_bf16 v[68:83], v[234:237], v[104:107], v[68:83]
	ds_read_b128 v[234:237], v213 offset:8192
	s_waitcnt lgkmcnt(4)
	v_mfma_f32_32x32x16_bf16 v[68:83], v[238:241], v[100:103], v[68:83]
	ds_read_b128 v[238:241], v214 offset:8192
	s_waitcnt lgkmcnt(4)
	v_mfma_f32_32x32x16_bf16 v[84:99], v[242:245], v[128:131], 0
	ds_read_b128 v[242:245], v215 offset:8192
	s_waitcnt lgkmcnt(4)
	v_mfma_f32_32x32x16_bf16 v[84:99], v[246:249], v[124:127], v[84:99]
	ds_read_b128 v[246:249], v216 offset:8192
	s_waitcnt lgkmcnt(4)
	v_mfma_f32_32x32x16_bf16 v[84:99], v[230:233], v[120:123], v[84:99]
	ds_read_b128 v[230:233], v217 offset:8192
	s_waitcnt lgkmcnt(4)
	v_mfma_f32_32x32x16_bf16 v[84:99], v[234:237], v[116:119], v[84:99]
	s_waitcnt lgkmcnt(3)
	v_mfma_f32_32x32x16_bf16 v[84:99], v[238:241], v[112:115], v[84:99]
	s_waitcnt lgkmcnt(2)
	v_mfma_f32_32x32x16_bf16 v[84:99], v[242:245], v[108:111], v[84:99]
	s_waitcnt lgkmcnt(1)
	v_mfma_f32_32x32x16_bf16 v[84:99], v[246:249], v[104:107], v[84:99]
	s_waitcnt lgkmcnt(0)
	v_mfma_f32_32x32x16_bf16 v[84:99], v[230:233], v[100:103], v[84:99]
	s_cbranch_vccnz .LBB0_582
	v_mov_b32_e32 v207, s22
	ds_read_b32 v207, v207 offset:1024
	s_mov_b32 s26, 0x3e0293ee
	s_andn2_b64 vcc, exec, s[4:5]
	s_cbranch_vccz .LBB0_583
	s_branch .LBB0_584

; #define LAS __attribute__((address_space(3)))
; DI unsigned pk2(float a, float b) { f32x2 v = {a, b}; bf16v2 r = __builtin_convertvector(v, bf16v2); return __builtin_bit_cast(unsigned, r); }
; #define MFMA32(a, b, cc) __builtin_amdgcn_mfma_f32_32x32x16_bf16((a), (b), (cc), 0, 0, 0)
; DI void attn_quad(LAS unsigned char* lds, const bf16_t* Z, bf16_t* BR, int c0  , int head, const LAS float* tbl, int tid) {
;     ...
;         float ps = 0.f; const float eoff = bc - mrun;
; #pragma unroll
;         for (int kb = 0; kb < 2; ++kb)
; #pragma unroll
;             for (int i = 0; i < 16; ++i) { s[kb][i] = __builtin_amdgcn_exp2f(__builtin_fmaf(s[kb][i], esc, eoff)); ps += s[kb][i]; }
;         ps += __shfl_xor(ps, 32);
;         lrun += ps;
; #pragma unroll
;         for (int kb = 0; kb < 2; ++kb)
; #pragma unroll
;             for (int st = 0; st < 2; ++st) {
;                 u32x4 pp; pp.x = pk2(s[kb][8 * st + 0], s[kb][8 * st + 1]); pp.y = pk2(s[kb][8 * st + 2], s[kb][8 * st + 3]); pp.z = pk2(s[kb][8 * st + 4], s[kb][8 * st + 5]); pp.w = pk2(s[kb][8 * st + 6], s[kb][8 * st + 7]);
;                 const bf16x8 pf = __builtin_bit_cast(bf16x8, pp);
; #pragma unroll
;                 for (int db = 0; db < 4; ++db) {
;                     s16x4 v2[2];
; #pragma unroll
;                     for (int t = 0; t < 2; ++t) {
;                         const int f = (q << 2) | ((2 * t + h) & 3);
;                         v2[t] = __builtin_amdgcn_ds_read_tr16_b64_v4i16((LAS s16x4*)(Vt + 256 * (32 * kb + 16 * st + 8 * t) + 16 * ((4 * db + vlo) ^ f)));
;                     }
;                     const bf16x8 vf = __builtin_shufflevector(v2[0], v2[1], 0, 1, 2, 3, 4, 5, 6, 7);
;                     o[db] = MFMA32(vf, pf, o[db]);
;                 }
;             }
.LBB0_586:
	v_sub_f32_e32 v207, v207, v149
	v_fma_f32 v68, s26, v68, v207
	v_exp_f32_e32 v209, v68
	v_fma_f32 v69, s26, v69, v207
	v_exp_f32_e32 v210, v69
	v_fma_f32 v69, s26, v70, v207
	v_exp_f32_e32 v211, v69
	v_fma_f32 v69, s26, v71, v207
	v_exp_f32_e32 v212, v69
	v_fma_f32 v69, s26, v72, v207
	v_add_f32_e32 v68, 0, v209
	v_exp_f32_e32 v213, v69
	v_fma_f32 v69, s26, v73, v207
	v_add_f32_e32 v68, v210, v68
	v_exp_f32_e32 v214, v69
	v_fma_f32 v69, s26, v74, v207
	v_add_f32_e32 v68, v211, v68
	v_exp_f32_e32 v74, v69
	v_fma_f32 v69, s26, v75, v207
	v_add_f32_e32 v68, v212, v68
	v_exp_f32_e32 v75, v69
	v_fma_f32 v69, s26, v76, v207
	v_add_f32_e32 v68, v213, v68
	v_exp_f32_e32 v215, v69
	v_fma_f32 v69, s26, v77, v207
	v_add_f32_e32 v68, v214, v68
	v_exp_f32_e32 v77, v69
	v_fma_f32 v69, s26, v78, v207
	v_add_f32_e32 v68, v74, v68
	v_exp_f32_e32 v216, v69
	v_fma_f32 v69, s26, v79, v207
	v_add_f32_e32 v68, v75, v68
	v_exp_f32_e32 v217, v69
	v_fma_f32 v69, s26, v80, v207
	v_add_f32_e32 v68, v215, v68
	v_exp_f32_e32 v230, v69
	v_fma_f32 v69, s26, v81, v207
	v_add_f32_e32 v68, v77, v68
	v_exp_f32_e32 v231, v69
	v_fma_f32 v69, s26, v82, v207
	v_add_f32_e32 v68, v216, v68
	v_exp_f32_e32 v232, v69
	v_fma_f32 v69, s26, v83, v207
	v_add_f32_e32 v68, v217, v68
	v_exp_f32_e32 v233, v69
	v_fma_f32 v69, s26, v84, v207
	v_add_f32_e32 v68, v230, v68
	v_exp_f32_e32 v234, v69
	v_fma_f32 v69, s26, v85, v207
	v_add_f32_e32 v68, v231, v68
	v_exp_f32_e32 v235, v69
	v_fma_f32 v69, s26, v86, v207
	v_add_f32_e32 v68, v232, v68
	v_exp_f32_e32 v86, v69
	v_fma_f32 v69, s26, v87, v207
	v_add_f32_e32 v68, v233, v68
	v_exp_f32_e32 v87, v69
	v_fma_f32 v69, s26, v88, v207
	v_add_f32_e32 v68, v234, v68
	v_exp_f32_e32 v88, v69
	v_fma_f32 v69, s26, v89, v207
	v_add_f32_e32 v68, v235, v68
	v_exp_f32_e32 v89, v69
	v_fma_f32 v69, s26, v90, v207
	v_add_f32_e32 v68, v86, v68
	v_exp_f32_e32 v90, v69
	v_fma_f32 v69, s26, v91, v207
	v_add_f32_e32 v68, v87, v68
	v_exp_f32_e32 v91, v69
	v_add_f32_e32 v68, v88, v68
	v_add_f32_e32 v68, v89, v68
	v_add_f32_e32 v68, v90, v68
	v_add_f32_e32 v69, v91, v68
	v_fma_f32 v68, s26, v92, v207
	v_exp_f32_e32 v68, v68
	v_fma_f32 v78, s26, v98, v207
	v_exp_f32_e32 v92, v78
	v_cvt_pk_bf16_f32 v81, v74, v75
	v_add_f32_e32 v70, v68, v69
	v_fma_f32 v69, s26, v93, v207
	v_exp_f32_e32 v69, v69
	v_add_u32_e32 v74, v143, v170
	v_add_u32_e32 v75, v143, v171
	s_waitcnt vmcnt(0)
	ds_read_b64_tr_b16 v[236:237], v74
	ds_read_b64_tr_b16 v[238:239], v75 offset:2048
	v_add_f32_e32 v71, v69, v70
	v_fma_f32 v70, s26, v94, v207
	v_exp_f32_e32 v70, v70
	v_cvt_pk_bf16_f32 v79, v211, v212
	v_cvt_pk_bf16_f32 v80, v213, v214
	v_add_u32_e32 v94, v143, v172
	v_add_f32_e32 v72, v70, v71
	v_fma_f32 v71, s26, v95, v207
	v_exp_f32_e32 v71, v71
	v_add_u32_e32 v95, v143, v173
	ds_read_b64_tr_b16 v[240:241], v94
	ds_read_b64_tr_b16 v[242:243], v95 offset:2048
	v_add_u32_e32 v98, v143, v169
	v_cvt_pk_bf16_f32 v68, v68, v69
	v_add_f32_e32 v73, v71, v72
	v_fma_f32 v72, s26, v96, v207
	v_exp_f32_e32 v72, v72
	v_add_u32_e32 v96, v143, v174
	v_cvt_pk_bf16_f32 v69, v70, v71
	v_add_f32_e32 v76, v72, v73
	v_fma_f32 v73, s26, v97, v207
	v_exp_f32_e32 v73, v73
	v_fmac_f32_e32 v207, s26, v99
	v_exp_f32_e32 v93, v207
	v_add_u32_e32 v97, v143, v175
	ds_read_b64_tr_b16 v[244:245], v96
	ds_read_b64_tr_b16 v[246:247], v97 offset:2048
	v_add_f32_e32 v76, v73, v76
	v_add_f32_e32 v76, v92, v76
	v_add_f32_e32 v76, v93, v76
	ds_bpermute_b32 v78, v208, v76
	s_waitcnt lgkmcnt(0)
	v_add_u32_e32 v99, v143, v176
	ds_read_b64_tr_b16 v[248:249], v98
	ds_read_b64_tr_b16 v[250:251], v99 offset:2048
	v_cvt_pk_bf16_f32 v70, v72, v73
	v_cvt_pk_bf16_f32 v71, v92, v93
	v_add_f32_e32 v76, v76, v78
	v_cvt_pk_bf16_f32 v78, v209, v210
	v_add_f32_e32 v145, v145, v76
	s_nop 0
	s_waitcnt lgkmcnt(6)
	v_mfma_f32_32x32x16_bf16 v[52:67], v[236:239], v[78:81], v[52:67]
	ds_read_b64_tr_b16 v[236:237], v74 offset:4096
	ds_read_b64_tr_b16 v[238:239], v75 offset:6144
	s_waitcnt lgkmcnt(6)
	v_mfma_f32_32x32x16_bf16 v[36:51], v[240:243], v[78:81], v[36:51]
	ds_read_b64_tr_b16 v[240:241], v94 offset:4096
	ds_read_b64_tr_b16 v[242:243], v95 offset:6144
	s_waitcnt lgkmcnt(6)
	v_mfma_f32_32x32x16_bf16 v[20:35], v[244:247], v[78:81], v[20:35]
	ds_read_b64_tr_b16 v[244:245], v96 offset:4096
	ds_read_b64_tr_b16 v[246:247], v97 offset:6144
	s_waitcnt lgkmcnt(6)
	v_mfma_f32_32x32x16_bf16 v[4:19], v[248:251], v[78:81], v[4:19]
	ds_read_b64_tr_b16 v[248:249], v98 offset:4096
	ds_read_b64_tr_b16 v[250:251], v99 offset:6144
	v_cvt_pk_bf16_f32 v78, v215, v77
	v_cvt_pk_bf16_f32 v79, v216, v217
	v_cvt_pk_bf16_f32 v80, v230, v231
	v_cvt_pk_bf16_f32 v81, v232, v233
	s_nop 0
	s_waitcnt lgkmcnt(6)
	v_mfma_f32_32x32x16_bf16 v[52:67], v[236:239], v[78:81], v[52:67]
	ds_read_b64_tr_b16 v[236:237], v74 offset:8192
	ds_read_b64_tr_b16 v[238:239], v75 offset:10240
	s_waitcnt lgkmcnt(6)
	v_mfma_f32_32x32x16_bf16 v[36:51], v[240:243], v[78:81], v[36:51]
	ds_read_b64_tr_b16 v[240:241], v94 offset:8192
	ds_read_b64_tr_b16 v[242:243], v95 offset:10240
	s_waitcnt lgkmcnt(6)
	v_mfma_f32_32x32x16_bf16 v[20:35], v[244:247], v[78:81], v[20:35]
	ds_read_b64_tr_b16 v[244:245], v96 offset:8192
	ds_read_b64_tr_b16 v[246:247], v97 offset:10240
	s_waitcnt lgkmcnt(6)
	v_mfma_f32_32x32x16_bf16 v[4:19], v[248:251], v[78:81], v[4:19]
	ds_read_b64_tr_b16 v[248:249], v74 offset:12288
	ds_read_b64_tr_b16 v[250:251], v75 offset:14336
	v_cvt_pk_bf16_f32 v78, v234, v235
	v_cvt_pk_bf16_f32 v79, v86, v87
	v_cvt_pk_bf16_f32 v80, v88, v89
	v_cvt_pk_bf16_f32 v81, v90, v91
	s_nop 0
	s_waitcnt lgkmcnt(6)
	v_mfma_f32_32x32x16_bf16 v[52:67], v[236:239], v[78:81], v[52:67]
	ds_read_b64_tr_b16 v[236:237], v94 offset:12288
	ds_read_b64_tr_b16 v[238:239], v95 offset:14336
	s_waitcnt lgkmcnt(6)
	v_mfma_f32_32x32x16_bf16 v[36:51], v[240:243], v[78:81], v[36:51]
	ds_read_b64_tr_b16 v[240:241], v98 offset:8192
	ds_read_b64_tr_b16 v[242:243], v99 offset:10240
	s_waitcnt lgkmcnt(6)
	v_mfma_f32_32x32x16_bf16 v[20:35], v[244:247], v[78:81], v[20:35]
	ds_read_b64_tr_b16 v[244:245], v96 offset:12288
	ds_read_b64_tr_b16 v[246:247], v97 offset:14336
	s_waitcnt lgkmcnt(6)
	v_mfma_f32_32x32x16_bf16 v[52:67], v[248:251], v[68:71], v[52:67]
	ds_read_b64_tr_b16 v[248:249], v98 offset:12288
	ds_read_b64_tr_b16 v[250:251], v99 offset:14336
	s_waitcnt lgkmcnt(6)
	v_mfma_f32_32x32x16_bf16 v[36:51], v[236:239], v[68:71], v[36:51]
	s_waitcnt lgkmcnt(4)
	v_mfma_f32_32x32x16_bf16 v[4:19], v[240:243], v[78:81], v[4:19]
	s_waitcnt lgkmcnt(2)
	v_mfma_f32_32x32x16_bf16 v[20:35], v[244:247], v[68:71], v[20:35]
	s_waitcnt lgkmcnt(0)
	v_mfma_f32_32x32x16_bf16 v[4:19], v[248:251], v[68:71], v[4:19]
; #define LAS __attribute__((address_space(3)))
; #define MFMA32(a, b, cc) __builtin_amdgcn_mfma_f32_32x32x16_bf16((a), (b), (cc), 0, 0, 0)
; DI void attn_quad(LAS unsigned char* lds, const bf16_t* Z, bf16_t* BR, int c0  , int head, const LAS float* tbl, int tid) {
;     ...
;     for (int j = j0; j < 12; ++j) {
;         if (j + 2 < 12) asm volatile("s_waitcnt vmcnt(8)" ::: "memory"); else if (j + 1 < 12) asm volatile("s_waitcnt vmcnt(4)" ::: "memory"); else asm volatile("s_waitcnt vmcnt(0)" ::: "memory");
;         asm volatile("s_waitcnt lgkmcnt(0)" ::: "memory"); __builtin_amdgcn_s_barrier(); asm volatile("" ::: "memory");
;         if (j + 3 < 12) AQ_ISSUE(j + 3);
;         const int jj = j - qc;
;         if (jj < 0 || jj > 8) continue;
;         const LAS unsigned char* Kt = lds + (j & 3) * 32768 + 256 * r;
;         const LAS unsigned char* Vt = lds + (j & 3) * 32768 + 16384 + 256 * (4 * h + q) + 8 * (p & 1);
;         f32x16 s[2];
; #pragma unroll
;         for (int kb = 0; kb < 2; ++kb) {
; #pragma unroll
;             for (int i = 0; i < 16; ++i) s[kb][i] = 0.f;
; #pragma unroll
;             for (int ks = 0; ks < 8; ++ks) { const bf16x8 kf = *(const LAS bf16x8*)(Kt + 8192 * kb + ((32 * ks) ^ kx)); s[kb] = MFMA32(kf, qf[ks], s[kb]); }
;         }
;         const bool cb = jj <= 5; const float bc = cb ? tbl[256] : 0.f, esc = cb ? sc : 1.0f;
.LBB0_587:
	s_waitcnt vmcnt(0)
	s_waitcnt lgkmcnt(0)
	s_barrier
	s_sub_i32 s26, 11, s23
	s_cmp_gt_u32 s26, 8
	s_cbranch_scc1 .LBB0_562
	v_add_u32_e32 v88, v140, v161
	ds_read_b128 v[214:217], v88
	v_add_u32_e32 v207, v140, v162
	ds_read_b128 v[230:233], v207
	v_add_u32_e32 v208, v140, v163
	ds_read_b128 v[234:237], v208
	v_add_u32_e32 v209, v140, v164
	ds_read_b128 v[238:241], v209
	v_add_u32_e32 v210, v140, v165
	ds_read_b128 v[242:245], v210
	v_add_u32_e32 v211, v140, v166
	ds_read_b128 v[246:249], v211
	v_add_u32_e32 v212, v140, v167
	v_add_u32_e32 v213, v140, v168
	s_waitcnt lgkmcnt(5)
	v_mfma_f32_32x32x16_bf16 v[68:83], v[214:217], v[128:131], 0
	ds_read_b128 v[214:217], v212
	s_cmp_gt_u32 s26, 5
	s_cselect_b64 s[4:5], -1, 0
	s_and_b64 vcc, exec, s[4:5]
	s_waitcnt lgkmcnt(5)
	v_mfma_f32_32x32x16_bf16 v[68:83], v[230:233], v[124:127], v[68:83]
	ds_read_b128 v[230:233], v213
	s_waitcnt lgkmcnt(5)
	v_mfma_f32_32x32x16_bf16 v[68:83], v[234:237], v[120:123], v[68:83]
	ds_read_b128 v[234:237], v88 offset:8192
	s_waitcnt lgkmcnt(5)
	v_mfma_f32_32x32x16_bf16 v[68:83], v[238:241], v[116:119], v[68:83]
	ds_read_b128 v[238:241], v207 offset:8192
	s_waitcnt lgkmcnt(5)
	v_mfma_f32_32x32x16_bf16 v[68:83], v[242:245], v[112:115], v[68:83]
	ds_read_b128 v[242:245], v208 offset:8192
	s_waitcnt lgkmcnt(5)
	v_mfma_f32_32x32x16_bf16 v[68:83], v[246:249], v[108:111], v[68:83]
	ds_read_b128 v[246:249], v209 offset:8192
	s_waitcnt lgkmcnt(5)
	v_mfma_f32_32x32x16_bf16 v[68:83], v[214:217], v[104:107], v[68:83]
	ds_read_b128 v[214:217], v210 offset:8192
	s_waitcnt lgkmcnt(5)
	v_mfma_f32_32x32x16_bf16 v[68:83], v[230:233], v[100:103], v[68:83]
	ds_read_b128 v[230:233], v211 offset:8192
	s_waitcnt lgkmcnt(5)
	v_mfma_f32_32x32x16_bf16 v[84:99], v[234:237], v[128:131], 0
	ds_read_b128 v[234:237], v212 offset:8192
	s_waitcnt lgkmcnt(5)
	v_mfma_f32_32x32x16_bf16 v[84:99], v[238:241], v[124:127], v[84:99]
	ds_read_b128 v[238:241], v213 offset:8192
	s_waitcnt lgkmcnt(5)
	v_mfma_f32_32x32x16_bf16 v[84:99], v[242:245], v[120:123], v[84:99]
	s_waitcnt lgkmcnt(4)
	v_mfma_f32_32x32x16_bf16 v[84:99], v[246:249], v[116:119], v[84:99]
	s_waitcnt lgkmcnt(3)
	v_mfma_f32_32x32x16_bf16 v[84:99], v[214:217], v[112:115], v[84:99]
	s_waitcnt lgkmcnt(2)
	v_mfma_f32_32x32x16_bf16 v[84:99], v[230:233], v[108:111], v[84:99]
	s_waitcnt lgkmcnt(1)
	v_mfma_f32_32x32x16_bf16 v[84:99], v[234:237], v[104:107], v[84:99]
	s_waitcnt lgkmcnt(0)
	v_mfma_f32_32x32x16_bf16 v[84:99], v[238:241], v[100:103], v[84:99]
	s_cbranch_vccnz .LBB0_590
	v_mov_b32_e32 v100, s22
	ds_read_b32 v100, v100 offset:1024
	s_mov_b32 s23, 0x3e0293ee
	s_andn2_b64 vcc, exec, s[4:5]
	s_cbranch_vccz .LBB0_591
	s_branch .LBB0_592

; #define LAS __attribute__((address_space(3)))
; #define MFMA32(a, b, cc) __builtin_amdgcn_mfma_f32_32x32x16_bf16((a), (b), (cc), 0, 0, 0)
; template <int MODE, class Src>
; DI void attn_item(LAS unsigned char* lds, const Src& src, const bf16_t* Qp  , bf16_t* Op  , int nband, int jj0, float sink_l2, const LAS float* tbl, int qbase, int tid) {
;     ...
;     for (int jj = jj0; jj < nband; ++jj) {
;         const bool last = (jj == nband - 1);
;         if (MODE) asm volatile("s_waitcnt vmcnt(8)" ::: "memory"); else asm volatile("s_waitcnt vmcnt(2)" ::: "memory");
;         __builtin_amdgcn_s_barrier(); asm volatile("" ::: "memory");
;         f32x16 s[2];
; #pragma unroll
;         for (int kb = 0; kb < 2; ++kb) {
; #pragma unroll
;             for (int i = 0; i < 16; ++i) s[kb][i] = 0.f;
; #pragma unroll
;             for (int ks = 0; ks < 8; ++ks) { const bf16x8 kf = *(const LAS bf16x8*)(Kt + 8192 * kb + ((32 * ks) ^ kx)); s[kb] = MFMA32(kf, qf[ks], s[kb]); }
;         }
;         asm volatile("s_waitcnt lgkmcnt(0)" ::: "memory"); __builtin_amdgcn_s_barrier(); asm volatile("" ::: "memory");
.LBB0_665:
	s_waitcnt vmcnt(8)
	s_barrier
	v_add_u32_e32 v2, v191, v161
	ds_read_b128 v[204:207], v2
	v_add_u32_e32 v8, v191, v162
	ds_read_b128 v[208:211], v8
	v_add_u32_e32 v9, v191, v163
	ds_read_b128 v[212:215], v9
	v_add_u32_e32 v10, v191, v164
	ds_read_b128 v[230:233], v10
	v_add_u32_e32 v11, v191, v165
	ds_read_b128 v[234:237], v11
	v_add_u32_e32 v12, v191, v166
	ds_read_b128 v[238:241], v12
	s_waitcnt lgkmcnt(5)
	v_mfma_f32_32x32x16_bf16 v[82:97], v[204:207], v[114:117], 0
	v_add_u32_e32 v13, v191, v167
	ds_read_b128 v[242:245], v13
	v_add_u32_e32 v14, v191, v168
	ds_read_b128 v[246:249], v14
	ds_read_b128 v[204:207], v2 offset:8192
	s_cmpk_lg_i32 s97, 0xfe00
	s_cselect_b64 s[58:59], -1, 0
	s_cmpk_eq_i32 s97, 0xfe00
	s_waitcnt lgkmcnt(7)
	v_mfma_f32_32x32x16_bf16 v[82:97], v[208:211], v[118:121], v[82:97]
	ds_read_b128 v[208:211], v8 offset:8192
	s_waitcnt lgkmcnt(7)
	v_mfma_f32_32x32x16_bf16 v[82:97], v[212:215], v[122:125], v[82:97]
	ds_read_b128 v[212:215], v9 offset:8192
	s_waitcnt lgkmcnt(7)
	v_mfma_f32_32x32x16_bf16 v[82:97], v[230:233], v[126:129], v[82:97]
	ds_read_b128 v[230:233], v10 offset:8192
	s_waitcnt lgkmcnt(7)
	v_mfma_f32_32x32x16_bf16 v[82:97], v[234:237], v[130:133], v[82:97]
	ds_read_b128 v[234:237], v11 offset:8192
	s_waitcnt lgkmcnt(7)
	v_mfma_f32_32x32x16_bf16 v[82:97], v[238:241], v[134:137], v[82:97]
	ds_read_b128 v[238:241], v12 offset:8192
	s_waitcnt lgkmcnt(7)
	v_mfma_f32_32x32x16_bf16 v[82:97], v[242:245], v[138:141], v[82:97]
	ds_read_b128 v[242:245], v13 offset:8192
	s_waitcnt lgkmcnt(7)
	v_mfma_f32_32x32x16_bf16 v[82:97], v[246:249], v[142:145], v[82:97]
	ds_read_b128 v[246:249], v14 offset:8192
	s_waitcnt lgkmcnt(7)
	v_mfma_f32_32x32x16_bf16 v[98:113], v[204:207], v[114:117], 0
	s_waitcnt lgkmcnt(6)
	v_mfma_f32_32x32x16_bf16 v[98:113], v[208:211], v[118:121], v[98:113]
	s_waitcnt lgkmcnt(5)
	v_mfma_f32_32x32x16_bf16 v[98:113], v[212:215], v[122:125], v[98:113]
	s_waitcnt lgkmcnt(4)
	v_mfma_f32_32x32x16_bf16 v[98:113], v[230:233], v[126:129], v[98:113]
	s_waitcnt lgkmcnt(3)
	v_mfma_f32_32x32x16_bf16 v[98:113], v[234:237], v[130:133], v[98:113]
	s_waitcnt lgkmcnt(2)
	v_mfma_f32_32x32x16_bf16 v[98:113], v[238:241], v[134:137], v[98:113]
	s_waitcnt lgkmcnt(1)
	v_mfma_f32_32x32x16_bf16 v[98:113], v[242:245], v[138:141], v[98:113]
	s_barrier
	s_waitcnt lgkmcnt(0)
	v_mfma_f32_32x32x16_bf16 v[98:113], v[246:249], v[142:145], v[98:113]
	s_cbranch_scc1 .LBB0_715
	s_cmp_lt_u32 s85, 7
	s_cselect_b64 s[42:43], -1, 0
	v_cndmask_b32_e64 v2, 0, 1, s[42:43]
	s_mov_b64 s[64:65], -1
	s_and_b64 vcc, exec, s[50:51]
	v_cmp_ne_u32_e64 s[42:43], 1, v2
	s_cbranch_vccz .LBB0_670
	s_mov_b64 s[62:63], 0x1a00
	s_and_b64 vcc, exec, s[42:43]
	s_mov_b64 s[60:61], s[4:5]
	s_cbranch_vccnz .LBB0_669
	s_ashr_i32 s55, s54, 31
	s_lshl_b64 s[60:61], s[54:55], 11
	s_add_u32 s60, s26, s60
	s_addc_u32 s61, s27, s61
	s_mov_b64 s[62:63], 0x400

; #define LAS __attribute__((address_space(3)))
; DI unsigned pk2(float a, float b) { f32x2 v = {a, b}; bf16v2 r = __builtin_convertvector(v, bf16v2); return __builtin_bit_cast(unsigned, r); }
; #define MFMA32(a, b, cc) __builtin_amdgcn_mfma_f32_32x32x16_bf16((a), (b), (cc), 0, 0, 0)
; template <int MODE, class Src>
; DI void attn_item(LAS unsigned char* lds, const Src& src, const bf16_t* Qp  , bf16_t* Op  , int nband, int jj0, float sink_l2, const LAS float* tbl, int qbase, int tid) {
;     ...
;         if (last) asm volatile("s_waitcnt vmcnt(0)" ::: "memory"); else { if (MODE) asm volatile("s_waitcnt vmcnt(8)" ::: "memory"); else asm volatile("s_waitcnt vmcnt(2)" ::: "memory"); }
;         __builtin_amdgcn_s_barrier(); asm volatile("" ::: "memory");
; #pragma unroll
;         for (int kb = 0; kb < 2; ++kb)
; #pragma unroll
;             for (int st = 0; st < 2; ++st) {
;                 u32x4 pp; pp.x = pk2(s[kb][8 * st + 0], s[kb][8 * st + 1]); pp.y = pk2(s[kb][8 * st + 2], s[kb][8 * st + 3]); pp.z = pk2(s[kb][8 * st + 4], s[kb][8 * st + 5]); pp.w = pk2(s[kb][8 * st + 6], s[kb][8 * st + 7]);
;                 const bf16x8 pf = __builtin_bit_cast(bf16x8, pp);
; #pragma unroll
;                 for (int db = 0; db < 4; ++db) {
;                     s16x4 v2[2];
; #pragma unroll
;                     for (int t = 0; t < 2; ++t) {
;                         const int f = (q << 2) | ((2 * t + h) & 3);
;                         v2[t] = __builtin_amdgcn_ds_read_tr16_b64_v4i16((LAS s16x4*)(Vt + 256 * (32 * kb + 16 * st + 8 * t) + 16 * ((4 * db + vlo) ^ f)));
;                     }
;                     const bf16x8 vf = __builtin_shufflevector(v2[0], v2[1], 0, 1, 2, 3, 4, 5, 6, 7);
;                     o[db] = MFMA32(vf, pf, o[db]);
;                 }
;             }
;         asm volatile("s_waitcnt lgkmcnt(0)" ::: "memory"); __builtin_amdgcn_s_barrier(); asm volatile("" ::: "memory");
;         if (!last) ATT_ISSUE(jj + 1, true);
.LBB0_725:
	s_barrier
	v_add_u32_e32 v102, v193, v170
	v_add_u32_e32 v103, v193, v171
	s_waitcnt vmcnt(0)
	ds_read_b64_tr_b16 v[206:207], v102
	ds_read_b64_tr_b16 v[208:209], v103 offset:2048
	v_cvt_pk_bf16_f32 v94, v153, v155
	v_cvt_pk_bf16_f32 v95, v157, v159
	v_cvt_pk_bf16_f32 v96, v195, v197
	v_cvt_pk_bf16_f32 v97, v204, v205
	v_add_u32_e32 v104, v193, v172
	v_add_u32_e32 v105, v193, v173
	ds_read_b64_tr_b16 v[210:211], v104
	ds_read_b64_tr_b16 v[212:213], v105 offset:2048
	s_waitcnt lgkmcnt(2)
	v_mfma_f32_32x32x16_bf16 v[66:81], v[206:209], v[94:97], v[66:81]
	v_add_u32_e32 v106, v193, v174
	v_add_u32_e32 v107, v193, v175
	ds_read_b64_tr_b16 v[214:215], v106
	ds_read_b64_tr_b16 v[216:217], v107 offset:2048
	ds_read_b64_tr_b16 v[230:231], v102 offset:4096
	ds_read_b64_tr_b16 v[232:233], v103 offset:6144
	ds_read_b64_tr_b16 v[234:235], v104 offset:4096
	ds_read_b64_tr_b16 v[236:237], v105 offset:6144
	ds_read_b64_tr_b16 v[238:239], v106 offset:4096
	ds_read_b64_tr_b16 v[240:241], v107 offset:6144
	ds_read_b64_tr_b16 v[242:243], v102 offset:8192
	ds_read_b64_tr_b16 v[244:245], v103 offset:10240
	ds_read_b64_tr_b16 v[246:247], v104 offset:8192
	ds_read_b64_tr_b16 v[248:249], v105 offset:10240
	v_add_u32_e32 v108, v193, v169
	v_add_u32_e32 v109, v193, v176
	v_cvt_pk_bf16_f32 v87, v87, v88
	s_waitcnt lgkmcnt(12)
	v_mfma_f32_32x32x16_bf16 v[50:65], v[210:213], v[94:97], v[50:65]
	ds_read_b64_tr_b16 v[206:207], v108
	ds_read_b64_tr_b16 v[208:209], v109 offset:2048
	v_cvt_pk_bf16_f32 v88, v89, v90
	v_cvt_pk_bf16_f32 v89, v91, v92
	v_cvt_pk_bf16_f32 v86, v85, v86
	v_cvt_pk_bf16_f32 v15, v15, v16
	v_cvt_pk_bf16_f32 v16, v17, v82
	s_waitcnt lgkmcnt(12)
	v_mfma_f32_32x32x16_bf16 v[34:49], v[214:217], v[94:97], v[34:49]
	ds_read_b64_tr_b16 v[210:211], v106 offset:8192
	ds_read_b64_tr_b16 v[212:213], v107 offset:10240
	v_cvt_pk_bf16_f32 v17, v83, v84
	v_cvt_pk_bf16_f32 v14, v13, v14
	v_cvt_pk_bf16_f32 v7, v7, v8
	v_cvt_pk_bf16_f32 v8, v9, v10
	s_waitcnt lgkmcnt(12)
	v_mfma_f32_32x32x16_bf16 v[66:81], v[230:233], v[86:89], v[66:81]
	ds_read_b64_tr_b16 v[214:215], v108 offset:4096
	ds_read_b64_tr_b16 v[216:217], v109 offset:6144
	v_cvt_pk_bf16_f32 v9, v11, v12
	v_cvt_pk_bf16_f32 v6, v2, v6
	s_andn2_b64 vcc, exec, s[58:59]
	s_waitcnt lgkmcnt(12)
	v_mfma_f32_32x32x16_bf16 v[50:65], v[234:237], v[86:89], v[50:65]
	ds_read_b64_tr_b16 v[230:231], v102 offset:12288
	ds_read_b64_tr_b16 v[232:233], v103 offset:14336
	s_waitcnt lgkmcnt(12)
	v_mfma_f32_32x32x16_bf16 v[34:49], v[238:241], v[86:89], v[34:49]
	ds_read_b64_tr_b16 v[234:235], v104 offset:12288
	ds_read_b64_tr_b16 v[236:237], v105 offset:14336
	s_waitcnt lgkmcnt(12)
	v_mfma_f32_32x32x16_bf16 v[66:81], v[242:245], v[14:17], v[66:81]
	ds_read_b64_tr_b16 v[238:239], v108 offset:8192
	ds_read_b64_tr_b16 v[240:241], v109 offset:10240
	s_waitcnt lgkmcnt(12)
	v_mfma_f32_32x32x16_bf16 v[50:65], v[246:249], v[14:17], v[50:65]
	ds_read_b64_tr_b16 v[242:243], v106 offset:12288
	ds_read_b64_tr_b16 v[244:245], v107 offset:14336
	s_waitcnt lgkmcnt(12)
	v_mfma_f32_32x32x16_bf16 v[18:33], v[206:209], v[94:97], v[18:33]
	ds_read_b64_tr_b16 v[246:247], v108 offset:12288
	ds_read_b64_tr_b16 v[248:249], v109 offset:14336
	s_waitcnt lgkmcnt(12)
	v_mfma_f32_32x32x16_bf16 v[34:49], v[210:213], v[14:17], v[34:49]
	s_waitcnt lgkmcnt(10)
	v_mfma_f32_32x32x16_bf16 v[18:33], v[214:217], v[86:89], v[18:33]
	s_waitcnt lgkmcnt(8)
	v_mfma_f32_32x32x16_bf16 v[66:81], v[230:233], v[6:9], v[66:81]
	s_waitcnt lgkmcnt(6)
	v_mfma_f32_32x32x16_bf16 v[50:65], v[234:237], v[6:9], v[50:65]
	s_waitcnt lgkmcnt(4)
	v_mfma_f32_32x32x16_bf16 v[18:33], v[238:241], v[14:17], v[18:33]
	s_waitcnt lgkmcnt(2)
	v_mfma_f32_32x32x16_bf16 v[34:49], v[242:245], v[6:9], v[34:49]
	s_barrier
	s_waitcnt lgkmcnt(0)
	v_mfma_f32_32x32x16_bf16 v[18:33], v[246:249], v[6:9], v[18:33]
	s_cbranch_vccnz .LBB0_664
	s_cmp_lt_u32 s85, 7
	s_cselect_b64 s[42:43], -1, 0
	v_cndmask_b32_e64 v2, 0, 1, s[42:43]
	s_mov_b64 s[58:59], 0x1a00
	s_and_b64 vcc, exec, s[40:41]
	v_cmp_ne_u32_e64 s[42:43], 1, v2
	s_mov_b64 s[62:63], s[56:57]
	s_mov_b64 s[60:61], 0x1a00
	s_cbranch_vccnz .LBB0_729
	s_and_b64 vcc, exec, s[42:43]
	s_mov_b64 s[62:63], s[8:9]
	s_cbranch_vccnz .LBB0_729
	s_ashr_i32 s55, s54, 31
	s_lshl_b64 s[60:61], s[54:55], 11
	s_add_u32 s62, s79, s60
	s_addc_u32 s63, s80, s61
	s_mov_b64 s[60:61], 0x400

; #define LAS __attribute__((address_space(3)))
; #define MFMA32(a, b, cc) __builtin_amdgcn_mfma_f32_32x32x16_bf16((a), (b), (cc), 0, 0, 0)
; template <int MODE, class Src>
; DI void attn_item(LAS unsigned char* lds, const Src& src, const bf16_t* Qp  , bf16_t* Op  , int nband, int jj0, float sink_l2, const LAS float* tbl, int qbase, int tid) {
;     ...
;         if (MODE) asm volatile("s_waitcnt vmcnt(8)" ::: "memory"); else asm volatile("s_waitcnt vmcnt(2)" ::: "memory");
;         __builtin_amdgcn_s_barrier(); asm volatile("" ::: "memory");
;         f32x16 s[2];
; #pragma unroll
;         for (int kb = 0; kb < 2; ++kb) {
; #pragma unroll
;             for (int i = 0; i < 16; ++i) s[kb][i] = 0.f;
; #pragma unroll
;             for (int ks = 0; ks < 8; ++ks) { const bf16x8 kf = *(const LAS bf16x8*)(Kt + 8192 * kb + ((32 * ks) ^ kx)); s[kb] = MFMA32(kf, qf[ks], s[kb]); }
;         }
;         asm volatile("s_waitcnt lgkmcnt(0)" ::: "memory"); __builtin_amdgcn_s_barrier(); asm volatile("" ::: "memory");
;         if (!last) ATT_ISSUE(jj + 1, false);
.LBB0_754:
	s_waitcnt vmcnt(2)
	s_barrier
	v_add_u32_e32 v2, v153, v161
	ds_read_b128 v[178:181], v2
	v_add_u32_e32 v8, v153, v162
	ds_read_b128 v[186:189], v8
	v_add_u32_e32 v9, v153, v163
	ds_read_b128 v[190:193], v9
	v_add_u32_e32 v10, v153, v164
	ds_read_b128 v[204:207], v10
	v_add_u32_e32 v11, v153, v165
	ds_read_b128 v[208:211], v11
	v_add_u32_e32 v12, v153, v166
	ds_read_b128 v[212:215], v12
	s_waitcnt lgkmcnt(5)
	v_mfma_f32_32x32x16_bf16 v[82:97], v[178:181], v[138:141], 0
	v_add_u32_e32 v13, v153, v167
	ds_read_b128 v[230:233], v13
	v_add_u32_e32 v14, v153, v168
	ds_read_b128 v[234:237], v14
	ds_read_b128 v[238:241], v2 offset:8192
	ds_read_b128 v[242:245], v8 offset:8192
	ds_read_b128 v[178:181], v9 offset:8192
	s_cmp_lg_u32 s18, 0x1a0000
	s_cselect_b64 s[34:35], -1, 0
	s_cmp_eq_u32 s18, 0x1a0000
	s_waitcnt lgkmcnt(9)
	v_mfma_f32_32x32x16_bf16 v[82:97], v[186:189], v[114:117], v[82:97]
	ds_read_b128 v[186:189], v10 offset:8192
	s_waitcnt lgkmcnt(9)
	v_mfma_f32_32x32x16_bf16 v[82:97], v[190:193], v[118:121], v[82:97]
	ds_read_b128 v[190:193], v11 offset:8192
	s_waitcnt lgkmcnt(9)
	v_mfma_f32_32x32x16_bf16 v[82:97], v[204:207], v[122:125], v[82:97]
	ds_read_b128 v[204:207], v12 offset:8192
	s_waitcnt lgkmcnt(9)
	v_mfma_f32_32x32x16_bf16 v[82:97], v[208:211], v[126:129], v[82:97]
	ds_read_b128 v[208:211], v13 offset:8192
	s_waitcnt lgkmcnt(9)
	v_mfma_f32_32x32x16_bf16 v[82:97], v[212:215], v[130:133], v[82:97]
	ds_read_b128 v[212:215], v14 offset:8192
	s_waitcnt lgkmcnt(9)
	v_mfma_f32_32x32x16_bf16 v[82:97], v[230:233], v[134:137], v[82:97]
	s_waitcnt lgkmcnt(8)
	v_mfma_f32_32x32x16_bf16 v[82:97], v[234:237], v[142:145], v[82:97]
	s_waitcnt lgkmcnt(7)
	v_mfma_f32_32x32x16_bf16 v[98:113], v[238:241], v[138:141], 0
	s_waitcnt lgkmcnt(6)
	v_mfma_f32_32x32x16_bf16 v[98:113], v[242:245], v[114:117], v[98:113]
	s_waitcnt lgkmcnt(5)
	v_mfma_f32_32x32x16_bf16 v[98:113], v[178:181], v[118:121], v[98:113]
	s_waitcnt lgkmcnt(4)
	v_mfma_f32_32x32x16_bf16 v[98:113], v[186:189], v[122:125], v[98:113]
	s_waitcnt lgkmcnt(3)
	v_mfma_f32_32x32x16_bf16 v[98:113], v[190:193], v[126:129], v[98:113]
	s_waitcnt lgkmcnt(2)
	v_mfma_f32_32x32x16_bf16 v[98:113], v[204:207], v[130:133], v[98:113]
	s_waitcnt lgkmcnt(1)
	v_mfma_f32_32x32x16_bf16 v[98:113], v[208:211], v[134:137], v[98:113]
	s_barrier
	s_waitcnt lgkmcnt(0)
	v_mfma_f32_32x32x16_bf16 v[98:113], v[212:215], v[142:145], v[98:113]
	s_cbranch_scc1 .LBB0_764
	v_readlane_b32 s40, v253, 61
	s_cmp_eq_u32 s18, 0
	v_readlane_b32 s41, v253, 62
	s_mov_b64 s[50:51], -1
	s_cselect_b64 s[38:39], -1, 0
	s_and_b64 vcc, exec, s[40:41]
	s_cbranch_vccz .LBB0_757
	s_and_b64 s[40:41], s[38:39], exec
	s_movk_i32 s12, 0x1a00
	s_cselect_b32 s12, 0x100, s12
	s_cselect_b32 s41, s52, s27
	s_cselect_b32 s40, s45, s26
	s_mov_b64 s[50:51], 0
	s_mov_b64 s[42:43], s[12:13]

; #define LAS __attribute__((address_space(3)))
; DI unsigned pk2(float a, float b) { f32x2 v = {a, b}; bf16v2 r = __builtin_convertvector(v, bf16v2); return __builtin_bit_cast(unsigned, r); }
; #define MFMA32(a, b, cc) __builtin_amdgcn_mfma_f32_32x32x16_bf16((a), (b), (cc), 0, 0, 0)
; template <int MODE, class Src>
; DI void attn_item(LAS unsigned char* lds, const Src& src, const bf16_t* Qp  , bf16_t* Op  , int nband, int jj0, float sink_l2, const LAS float* tbl, int qbase, int tid) {
;     ...
;         if (last) asm volatile("s_waitcnt vmcnt(0)" ::: "memory"); else { if (MODE) asm volatile("s_waitcnt vmcnt(8)" ::: "memory"); else asm volatile("s_waitcnt vmcnt(2)" ::: "memory"); }
;         __builtin_amdgcn_s_barrier(); asm volatile("" ::: "memory");
; #pragma unroll
;         for (int kb = 0; kb < 2; ++kb)
; #pragma unroll
;             for (int st = 0; st < 2; ++st) {
;                 u32x4 pp; pp.x = pk2(s[kb][8 * st + 0], s[kb][8 * st + 1]); pp.y = pk2(s[kb][8 * st + 2], s[kb][8 * st + 3]); pp.z = pk2(s[kb][8 * st + 4], s[kb][8 * st + 5]); pp.w = pk2(s[kb][8 * st + 6], s[kb][8 * st + 7]);
;                 const bf16x8 pf = __builtin_bit_cast(bf16x8, pp);
; #pragma unroll
;                 for (int db = 0; db < 4; ++db) {
;                     s16x4 v2[2];
; #pragma unroll
;                     for (int t = 0; t < 2; ++t) {
;                         const int f = (q << 2) | ((2 * t + h) & 3);
;                         v2[t] = __builtin_amdgcn_ds_read_tr16_b64_v4i16((LAS s16x4*)(Vt + 256 * (32 * kb + 16 * st + 8 * t) + 16 * ((4 * db + vlo) ^ f)));
;                     }
;                     const bf16x8 vf = __builtin_shufflevector(v2[0], v2[1], 0, 1, 2, 3, 4, 5, 6, 7);
;                     o[db] = MFMA32(vf, pf, o[db]);
;                 }
;             }
;         asm volatile("s_waitcnt lgkmcnt(0)" ::: "memory"); __builtin_amdgcn_s_barrier(); asm volatile("" ::: "memory");
;         if (!last) ATT_ISSUE(jj + 1, true);
.LBB0_770:
	s_barrier
	v_add_u32_e32 v2, v155, v170
	v_add_u32_e32 v102, v155, v171
	s_waitcnt vmcnt(0)
	ds_read_b64_tr_b16 v[186:187], v2
	ds_read_b64_tr_b16 v[188:189], v102 offset:2048
	v_cvt_pk_bf16_f32 v94, v159, v177
	v_cvt_pk_bf16_f32 v95, v178, v179
	v_cvt_pk_bf16_f32 v96, v180, v181
	v_cvt_pk_bf16_f32 v97, v182, v183
	v_add_u32_e32 v103, v155, v172
	v_add_u32_e32 v104, v155, v173
	ds_read_b64_tr_b16 v[190:191], v103
	ds_read_b64_tr_b16 v[192:193], v104 offset:2048
	s_waitcnt lgkmcnt(2)
	v_mfma_f32_32x32x16_bf16 v[66:81], v[186:189], v[94:97], v[66:81]
	v_add_u32_e32 v105, v155, v174
	v_add_u32_e32 v106, v155, v175
	ds_read_b64_tr_b16 v[204:205], v105
	ds_read_b64_tr_b16 v[206:207], v106 offset:2048
	ds_read_b64_tr_b16 v[208:209], v2 offset:4096
	ds_read_b64_tr_b16 v[210:211], v102 offset:6144
	ds_read_b64_tr_b16 v[212:213], v103 offset:4096
	ds_read_b64_tr_b16 v[214:215], v104 offset:6144
	ds_read_b64_tr_b16 v[230:231], v105 offset:4096
	ds_read_b64_tr_b16 v[232:233], v106 offset:6144
	ds_read_b64_tr_b16 v[234:235], v2 offset:8192
	ds_read_b64_tr_b16 v[236:237], v102 offset:10240
	ds_read_b64_tr_b16 v[238:239], v103 offset:8192
	ds_read_b64_tr_b16 v[240:241], v104 offset:10240
	v_add_u32_e32 v107, v155, v169
	v_add_u32_e32 v108, v155, v176
	v_cvt_pk_bf16_f32 v86, v86, v87
	s_waitcnt lgkmcnt(12)
	v_mfma_f32_32x32x16_bf16 v[50:65], v[190:193], v[94:97], v[50:65]
	ds_read_b64_tr_b16 v[186:187], v107
	ds_read_b64_tr_b16 v[188:189], v108 offset:2048
	v_cvt_pk_bf16_f32 v87, v88, v89
	v_cvt_pk_bf16_f32 v88, v90, v91
	v_cvt_pk_bf16_f32 v89, v92, v93
	v_cvt_pk_bf16_f32 v14, v14, v15
	v_cvt_pk_bf16_f32 v15, v16, v17
	s_waitcnt lgkmcnt(12)
	v_mfma_f32_32x32x16_bf16 v[34:49], v[204:207], v[94:97], v[34:49]
	ds_read_b64_tr_b16 v[190:191], v105 offset:8192
	ds_read_b64_tr_b16 v[192:193], v106 offset:10240
	v_cvt_pk_bf16_f32 v16, v82, v83
	v_cvt_pk_bf16_f32 v17, v84, v85
	v_cvt_pk_bf16_f32 v6, v6, v7
	v_cvt_pk_bf16_f32 v7, v8, v9
	s_waitcnt lgkmcnt(12)
	v_mfma_f32_32x32x16_bf16 v[66:81], v[208:211], v[86:89], v[66:81]
	ds_read_b64_tr_b16 v[204:205], v107 offset:4096
	ds_read_b64_tr_b16 v[206:207], v108 offset:6144
	v_cvt_pk_bf16_f32 v8, v10, v11
	v_cvt_pk_bf16_f32 v9, v12, v13
	s_andn2_b64 vcc, exec, s[34:35]
	s_waitcnt lgkmcnt(12)
	v_mfma_f32_32x32x16_bf16 v[50:65], v[212:215], v[86:89], v[50:65]
	ds_read_b64_tr_b16 v[208:209], v2 offset:12288
	ds_read_b64_tr_b16 v[210:211], v102 offset:14336
	s_waitcnt lgkmcnt(12)
	v_mfma_f32_32x32x16_bf16 v[34:49], v[230:233], v[86:89], v[34:49]
	ds_read_b64_tr_b16 v[212:213], v103 offset:12288
	ds_read_b64_tr_b16 v[214:215], v104 offset:14336
	s_waitcnt lgkmcnt(12)
	v_mfma_f32_32x32x16_bf16 v[66:81], v[234:237], v[14:17], v[66:81]
	ds_read_b64_tr_b16 v[230:231], v107 offset:8192
	ds_read_b64_tr_b16 v[232:233], v108 offset:10240
	s_waitcnt lgkmcnt(12)
	v_mfma_f32_32x32x16_bf16 v[50:65], v[238:241], v[14:17], v[50:65]
	ds_read_b64_tr_b16 v[234:235], v105 offset:12288
	ds_read_b64_tr_b16 v[236:237], v106 offset:14336
	s_waitcnt lgkmcnt(12)
	v_mfma_f32_32x32x16_bf16 v[18:33], v[186:189], v[94:97], v[18:33]
	ds_read_b64_tr_b16 v[238:239], v107 offset:12288
	ds_read_b64_tr_b16 v[240:241], v108 offset:14336
	s_waitcnt lgkmcnt(12)
	v_mfma_f32_32x32x16_bf16 v[34:49], v[190:193], v[14:17], v[34:49]
	s_waitcnt lgkmcnt(10)
	v_mfma_f32_32x32x16_bf16 v[18:33], v[204:207], v[86:89], v[18:33]
	s_waitcnt lgkmcnt(8)
	v_mfma_f32_32x32x16_bf16 v[66:81], v[208:211], v[6:9], v[66:81]
	s_waitcnt lgkmcnt(6)
	v_mfma_f32_32x32x16_bf16 v[50:65], v[212:215], v[6:9], v[50:65]
	s_waitcnt lgkmcnt(4)
	v_mfma_f32_32x32x16_bf16 v[18:33], v[230:233], v[14:17], v[18:33]
	s_waitcnt lgkmcnt(2)
	v_mfma_f32_32x32x16_bf16 v[34:49], v[234:237], v[6:9], v[34:49]
	s_barrier
	s_waitcnt lgkmcnt(0)
	v_mfma_f32_32x32x16_bf16 v[18:33], v[238:241], v[6:9], v[18:33]
	s_cbranch_vccnz .LBB0_753
	v_readlane_b32 s38, v253, 61
	s_cmp_eq_u32 s18, 0
	v_readlane_b32 s39, v253, 62
	s_mov_b64 s[42:43], -1
	s_cselect_b64 s[34:35], -1, 0
	s_and_b64 vcc, exec, s[38:39]
	s_cbranch_vccz .LBB0_773
	s_and_b64 s[38:39], s[34:35], exec
	s_movk_i32 s12, 0x1a00
	s_cselect_b32 s12, 0x100, s12
	s_cselect_b32 s39, s56, s54
	s_cselect_b32 s38, s55, s53
	s_mov_b64 s[42:43], 0
	s_mov_b64 s[40:41], s[12:13]
